# EpiUp epilogue: conv/bias vectors prefetched before the K loop and staged through LDS, packed f32 math in gelu
# speedup vs baseline: 1.0126x; 1.0031x over previous
.LBB0_1149:
	s_ashr_i32 s47, s46, 31
	s_lshl_b64 s[48:49], s[46:47], 19
	s_add_u32 s48, s60, s48
	s_addc_u32 s49, s61, s49
	s_and_b64 s[50:51], s[8:9], exec
	s_cselect_b32 s3, s49, s53
	s_cselect_b32 s11, s48, s52
	s_ashr_i32 s45, s44, 31
	s_lshl_b64 s[50:51], s[44:45], 19
	s_add_u32 s50, s62, s50
	s_addc_u32 s51, s63, s51
	s_and_b64 s[56:57], s[8:9], exec
	s_cselect_b32 s33, s51, s55
	s_cselect_b32 s45, s50, s54
	s_add_u32 s52, s52, 0x40080
	s_addc_u32 s53, s53, 0
	s_add_u32 s47, s54, 0x100
	v_mov_b32_e32 v0, 0
	s_addc_u32 s58, s55, 0
	s_mov_b32 s59, -2
	v_mov_b32_e32 v1, v0
	s_waitcnt vmcnt(0)
	v_mov_b32_e32 v2, v0
	v_mov_b32_e32 v3, v0
	v_mov_b32_e32 v4, v0
	v_mov_b32_e32 v5, v0
	v_mov_b32_e32 v6, v0
	v_mov_b32_e32 v7, v0
	v_mov_b32_e32 v8, v0
	v_mov_b32_e32 v9, v0
	v_mov_b32_e32 v10, v0
	v_mov_b32_e32 v11, v0
	s_waitcnt vmcnt(0)
	v_mov_b32_e32 v16, v0
	v_mov_b32_e32 v17, v0
	v_mov_b32_e32 v18, v0
	v_mov_b32_e32 v19, v0
	v_mov_b32_e32 v24, v0
	v_mov_b32_e32 v25, v0
	v_mov_b32_e32 v26, v0
	v_mov_b32_e32 v27, v0
	v_mov_b32_e32 v32, v0
	v_mov_b32_e32 v33, v0
	v_mov_b32_e32 v34, v0
	v_mov_b32_e32 v35, v0
	v_mov_b32_e32 v40, v0
	v_mov_b32_e32 v41, v0
	v_mov_b32_e32 v42, v0
	v_mov_b32_e32 v43, v0
	v_mov_b32_e32 v48, v0
	v_mov_b32_e32 v49, v0
	v_mov_b32_e32 v50, v0
	v_mov_b32_e32 v51, v0
	v_mov_b32_e32 v12, v0
	v_mov_b32_e32 v13, v0
	v_mov_b32_e32 v14, v0
	v_mov_b32_e32 v15, v0
	v_mov_b32_e32 v20, v0
	v_mov_b32_e32 v21, v0
	v_mov_b32_e32 v22, v0
	v_mov_b32_e32 v23, v0
	v_mov_b32_e32 v28, v0
	v_mov_b32_e32 v29, v0
	v_mov_b32_e32 v30, v0
	v_mov_b32_e32 v31, v0
	v_mov_b32_e32 v36, v0
	v_mov_b32_e32 v37, v0
	v_mov_b32_e32 v38, v0
	v_mov_b32_e32 v39, v0
	v_mov_b32_e32 v44, v0
	v_mov_b32_e32 v45, v0
	v_mov_b32_e32 v46, v0
	v_mov_b32_e32 v47, v0
	v_mov_b32_e32 v52, v0
	v_mov_b32_e32 v53, v0
	v_mov_b32_e32 v54, v0
	v_mov_b32_e32 v55, v0
	v_mov_b32_e32 v56, v0
	v_mov_b32_e32 v57, v0
	v_mov_b32_e32 v58, v0
	v_mov_b32_e32 v59, v0
	v_mov_b32_e32 v60, v0
	v_mov_b32_e32 v61, v0
	v_mov_b32_e32 v62, v0
	v_mov_b32_e32 v63, v0
	v_mov_b32_e32 v64, v0
	v_mov_b32_e32 v65, v0
	v_mov_b32_e32 v66, v0
	v_mov_b32_e32 v67, v0
	v_mov_b32_e32 v68, v0
	v_mov_b32_e32 v69, v0
	v_mov_b32_e32 v70, v0
	v_mov_b32_e32 v71, v0
	v_mov_b32_e32 v72, v0
	v_mov_b32_e32 v73, v0
	v_mov_b32_e32 v74, v0
	v_mov_b32_e32 v75, v0
	v_mov_b32_e32 v80, v0
	v_mov_b32_e32 v81, v0
	v_mov_b32_e32 v82, v0
	v_mov_b32_e32 v83, v0
	v_mov_b32_e32 v88, v0
	v_mov_b32_e32 v89, v0
	v_mov_b32_e32 v90, v0
	v_mov_b32_e32 v91, v0
	v_mov_b32_e32 v96, v0
	v_mov_b32_e32 v97, v0
	v_mov_b32_e32 v98, v0
	v_mov_b32_e32 v99, v0
	v_mov_b32_e32 v104, v0
	v_mov_b32_e32 v105, v0
	v_mov_b32_e32 v106, v0
	v_mov_b32_e32 v107, v0
	v_mov_b32_e32 v116, v0
	v_mov_b32_e32 v117, v0
	v_mov_b32_e32 v118, v0
	v_mov_b32_e32 v119, v0
	v_mov_b32_e32 v76, v0
	v_mov_b32_e32 v77, v0
	v_mov_b32_e32 v78, v0
	v_mov_b32_e32 v79, v0
	v_mov_b32_e32 v84, v0
	v_mov_b32_e32 v85, v0
	v_mov_b32_e32 v86, v0
	v_mov_b32_e32 v87, v0
	v_mov_b32_e32 v92, v0
	v_mov_b32_e32 v93, v0
	v_mov_b32_e32 v94, v0
	v_mov_b32_e32 v95, v0
	v_mov_b32_e32 v100, v0
	v_mov_b32_e32 v101, v0
	v_mov_b32_e32 v102, v0
	v_mov_b32_e32 v103, v0
	v_mov_b32_e32 v108, v0
	v_mov_b32_e32 v109, v0
	v_mov_b32_e32 v110, v0
	v_mov_b32_e32 v111, v0
	v_mov_b32_e32 v112, v0
	v_mov_b32_e32 v113, v0
	v_mov_b32_e32 v114, v0
	v_mov_b32_e32 v115, v0
	v_mov_b32_e32 v120, v0
	v_mov_b32_e32 v121, v0
	v_mov_b32_e32 v122, v0
	v_mov_b32_e32 v123, v0
	v_mov_b32_e32 v124, v0
	v_mov_b32_e32 v125, v0
	v_mov_b32_e32 v126, v0
	v_mov_b32_e32 v127, v0
	v_lshrrev_b32_e32 v242, 5, v192
	v_and_b32_e32 v243, 31, v192
	v_mov_b32_e32 v241, s10
	v_lshlrev_b32_e32 v241, 9, v241
	v_lshl_add_u32 v243, v243, 4, v241
	v_add_u32_e32 v241, 0x2c00, v243
	v_cmp_eq_u32_e32 vcc, 0, v242
	s_nop 1
	s_mov_b64 exec, vcc
	global_load_dwordx4 v[244:247], v243, s[16:17]
	s_mov_b64 exec, -1
	v_cmp_eq_u32_e32 vcc, 1, v242
	s_nop 1
	s_mov_b64 exec, vcc
	global_load_dwordx4 v[244:247], v241, s[16:17]
	s_mov_b64 exec, -1
	v_cmp_eq_u32_e32 vcc, 2, v242
	s_nop 1
	s_mov_b64 exec, vcc
	global_load_dwordx4 v[244:247], v243, s[4:5]
	s_mov_b64 exec, -1
	v_cmp_eq_u32_e32 vcc, 3, v242
	s_nop 1
	s_mov_b64 exec, vcc
	global_load_dwordx4 v[244:247], v243, s[30:31]
	s_mov_b64 exec, -1
	v_cmp_eq_u32_e32 vcc, 4, v242
	s_nop 1
	s_mov_b64 exec, vcc
	global_load_dwordx4 v[244:247], v243, s[18:19]
	s_mov_b64 exec, -1
	v_cmp_eq_u32_e32 vcc, 5, v242
	s_nop 1
	s_mov_b64 exec, vcc
	global_load_dwordx4 v[244:247], v243, s[34:35]
	s_mov_b64 exec, -1
	v_cmp_eq_u32_e32 vcc, 6, v242
	s_nop 1
	s_mov_b64 exec, vcc
	global_load_dwordx4 v[244:247], v243, s[36:37]
	s_mov_b64 exec, -1
	v_cmp_eq_u32_e32 vcc, 7, v242
	s_nop 1
	s_mov_b64 exec, vcc
	global_load_dwordx4 v[244:247], v243, s[38:39]
	s_mov_b64 exec, -1
	v_cmp_eq_u32_e32 vcc, 8, v242
	s_nop 1
	s_mov_b64 exec, vcc
	global_load_dwordx4 v[244:247], v243, s[40:41]
	s_mov_b64 exec, -1
	v_cmp_eq_u32_e32 vcc, 9, v242
	s_nop 1
	s_mov_b64 exec, vcc
	global_load_dwordx4 v[244:247], v243, s[42:43]
	s_mov_b64 exec, -1

.Lepi9_prompt:
	v_and_b32_e32 v234, 0xf, v192
	v_cmp_gt_u32_e64 s[52:53], 2, v234
	v_cmp_lt_u32_e64 s[54:55], 13, v234
	v_readfirstlane_b32 s33, v192
	v_bfe_u32 v241, v192, 4, 2
	v_bfe_u32 v242, v192, 6, 2
	s_lshr_b32 s33, s33, 8
	v_lshlrev_b32_e32 v240, 0x5, v242
	v_lshl_add_u32 v240, v241, 3, v240
	s_lshl_b32 s11, s10, 7
	v_lshrrev_b32_e32 v237, 0x6, v192
	v_lshlrev_b32_e32 v237, 0xa, v237
	v_bfe_u32 v238, v192, 4, 2
	v_lshl_add_u32 v237, v238, 7, v237
	v_lshl_add_u32 v237, v234, 6, v237
	v_add_u32_e32 v237, 0x1fc80, v237
	s_waitcnt vmcnt(8)
	v_lshlrev_b32_e32 v241, 0x4, v192
	v_add_u32_e32 v241, 0x22000, v241
	v_cmp_gt_u32_e32 vcc, 0x140, v192
	s_nop 1
	s_mov_b64 exec, vcc
	ds_write_b128 v241, v[244:247]
	s_mov_b64 exec, -1
	v_lshlrev_b32_e32 v152, 0x2, v240
	v_add_u32_e32 v152, 0x22000, v152
	v_mov_b32_e32 v166, 0x3d372713
	v_mov_b32_e32 v167, 0x3d372713
	v_mov_b32_e32 v250, 0xc0135761
	v_mov_b32_e32 v251, 0xc0135761
	s_mov_b64 exec, s[54:55]
	ds_write_b128 v237, v[84:87]
	ds_write_b128 v237, v[76:79] offset:16
	ds_write_b128 v237, v[68:71] offset:32
	ds_write_b128 v237, v[64:67] offset:48
	ds_write_b128 v237, v[20:23] offset:512
	ds_write_b128 v237, v[12:15] offset:528
	ds_write_b128 v237, v[4:7] offset:544
	ds_write_b128 v237, v[0:3] offset:560
	s_mov_b64 exec, -1
	v_xor_b32_e32 v238, 0x1000, v237
	s_lshl_b32 s3, s33, 9
	v_add_u32_e32 v239, s3, v238
	v_lshrrev_b32_e32 v235, 0x8, v192
	v_lshl_add_u32 v235, v235, 6, v234
	v_mul_u32_u24_e32 v235, 0x1600, v235
	v_lshl_add_u32 v235, v240, 1, v235
	s_mul_i32 s3, s2, 0x160000
	s_add_u32 s56, s24, s3
	s_addc_u32 s57, s25, 0
	s_lshl_b32 s3, s10, 8
	s_add_u32 s56, s56, s3
	s_addc_u32 s57, s57, 0
	v_mul_u32_u24_e32 v236, 0x2c00, v234
	v_lshl_add_u32 v236, v240, 1, v236
	s_waitcnt lgkmcnt(0)
	s_barrier
	ds_read_b128 v[226:229], v152
	ds_read_b128 v[230:233], v152 offset:512
	ds_read_b128 v[206:209], v152 offset:1024
	ds_read_b128 v[222:225], v152 offset:1536
	ds_read_b128 v[194:197], v152 offset:2048
	ds_read_b128 v[198:201], v152 offset:2560
	ds_read_b128 v[202:205], v152 offset:3072
	ds_read_b128 v[210:213], v152 offset:3584
	ds_read_b128 v[214:217], v152 offset:4096
	ds_read_b128 v[218:221], v152 offset:4608
	ds_read_b128 v[128:131], v238
	ds_read_b128 v[132:135], v238 offset:32
	ds_read_b128 v[136:139], v239
	ds_read_b128 v[140:143], v239 offset:32
	s_lshl_b32 s3, s2, 2
	s_add_u32 s3, s3, 2
	s_mul_i32 s3, s3, 0x2c00
	s_add_u32 s58, s14, s3
	s_addc_u32 s59, s15, 0
	s_lshl_b32 s3, s10, 8
	s_add_u32 s58, s58, s3
	s_addc_u32 s59, s59, 0
	s_waitcnt lgkmcnt(0)
	s_cmp_lg_u32 s33, 0
	s_cbranch_scc1 .Lepi9_wr1_1
	s_mov_b64 exec, s[52:53]
	v_add_f32_e32 v184, v124, v226
	v_add_f32_e32 v185, v125, v227
	v_add_f32_e32 v186, v126, v228
	v_add_f32_e32 v187, v127, v229
	v_cvt_pk_bf16_f32 v184, v184, v185
	v_cvt_pk_bf16_f32 v185, v186, v187
	global_store_dwordx2 v236, v[184:185], s[58:59]
	v_add_f32_e32 v188, v116, v230
	v_add_f32_e32 v189, v117, v231
	v_add_f32_e32 v190, v118, v232
	v_add_f32_e32 v191, v119, v233
	v_cvt_pk_bf16_f32 v188, v188, v189
	v_cvt_pk_bf16_f32 v189, v190, v191
	v_add_u32_e32 v241, 0x1600, v236
	global_store_dwordx2 v241, v[188:189], s[58:59]
	s_mov_b64 exec, -1
	s_branch .Lepi9_wrend_1

.Lepi9_wrend_1:
	v_add_f32_e32 v180, v194, v198
	v_add_f32_e32 v181, v195, v199
	v_add_f32_e32 v182, v196, v200
	v_add_f32_e32 v183, v197, v201
	v_add_f32_e32 v180, v180, v202
	v_add_f32_e32 v181, v181, v203
	v_add_f32_e32 v182, v182, v204
	v_add_f32_e32 v183, v183, v205
	v_fma_f32 v206, v226, v180, v206
	v_fma_f32 v207, v227, v181, v207
	v_fma_f32 v208, v228, v182, v208
	v_fma_f32 v209, v229, v183, v209
	v_add_f32_e32 v180, v210, v214
	v_add_f32_e32 v181, v211, v215
	v_add_f32_e32 v182, v212, v216
	v_add_f32_e32 v183, v213, v217
	v_add_f32_e32 v180, v180, v218
	v_add_f32_e32 v181, v181, v219
	v_add_f32_e32 v182, v182, v220
	v_add_f32_e32 v183, v183, v221
	v_fma_f32 v222, v230, v180, v222
	v_fma_f32 v223, v231, v181, v223
	v_fma_f32 v224, v232, v182, v224
	v_fma_f32 v225, v233, v183, v225
	s_waitcnt lgkmcnt(0)
	v_pk_fma_f32 v[172:173], v[202:203], v[84:85], v[206:207]
	v_pk_fma_f32 v[174:175], v[204:205], v[86:87], v[208:209]
	v_pk_fma_f32 v[176:177], v[218:219], v[68:69], v[222:223]
	v_pk_fma_f32 v[178:179], v[220:221], v[70:71], v[224:225]
	v_fmac_f32_dpp v172, v84, v198 row_shr:1 row_mask:0xf bank_mask:0xf
	v_fmac_f32_dpp v173, v85, v199 row_shr:1 row_mask:0xf bank_mask:0xf
	v_fmac_f32_dpp v174, v86, v200 row_shr:1 row_mask:0xf bank_mask:0xf
	v_fmac_f32_dpp v175, v87, v201 row_shr:1 row_mask:0xf bank_mask:0xf
	v_fmac_f32_dpp v176, v68, v214 row_shr:1 row_mask:0xf bank_mask:0xf
	v_fmac_f32_dpp v177, v69, v215 row_shr:1 row_mask:0xf bank_mask:0xf
	v_fmac_f32_dpp v178, v70, v216 row_shr:1 row_mask:0xf bank_mask:0xf
	v_fmac_f32_dpp v179, v71, v217 row_shr:1 row_mask:0xf bank_mask:0xf
	v_fmac_f32_dpp v172, v84, v194 row_shr:2 row_mask:0xf bank_mask:0xf
	v_fmac_f32_dpp v173, v85, v195 row_shr:2 row_mask:0xf bank_mask:0xf
	v_fmac_f32_dpp v174, v86, v196 row_shr:2 row_mask:0xf bank_mask:0xf
	v_fmac_f32_dpp v175, v87, v197 row_shr:2 row_mask:0xf bank_mask:0xf
	v_fmac_f32_dpp v176, v68, v210 row_shr:2 row_mask:0xf bank_mask:0xf
	v_fmac_f32_dpp v177, v69, v211 row_shr:2 row_mask:0xf bank_mask:0xf
	v_fmac_f32_dpp v178, v70, v212 row_shr:2 row_mask:0xf bank_mask:0xf
	v_fmac_f32_dpp v179, v71, v213 row_shr:2 row_mask:0xf bank_mask:0xf
	v_fmac_f32_dpp v172, v100, v198 row_shl:15 row_mask:0xf bank_mask:0xf
	v_fmac_f32_dpp v173, v101, v199 row_shl:15 row_mask:0xf bank_mask:0xf
	v_fmac_f32_dpp v174, v102, v200 row_shl:15 row_mask:0xf bank_mask:0xf
	v_fmac_f32_dpp v175, v103, v201 row_shl:15 row_mask:0xf bank_mask:0xf
	v_fmac_f32_dpp v176, v80, v214 row_shl:15 row_mask:0xf bank_mask:0xf
	v_fmac_f32_dpp v177, v81, v215 row_shl:15 row_mask:0xf bank_mask:0xf
	v_fmac_f32_dpp v178, v82, v216 row_shl:15 row_mask:0xf bank_mask:0xf
	v_fmac_f32_dpp v179, v83, v217 row_shl:15 row_mask:0xf bank_mask:0xf
	v_fmac_f32_dpp v172, v100, v194 row_shl:14 row_mask:0xf bank_mask:0xf
	v_fmac_f32_dpp v173, v101, v195 row_shl:14 row_mask:0xf bank_mask:0xf
	v_fmac_f32_dpp v174, v102, v196 row_shl:14 row_mask:0xf bank_mask:0xf
	v_fmac_f32_dpp v175, v103, v197 row_shl:14 row_mask:0xf bank_mask:0xf
	v_fmac_f32_dpp v176, v80, v210 row_shl:14 row_mask:0xf bank_mask:0xf
	v_fmac_f32_dpp v177, v81, v211 row_shl:14 row_mask:0xf bank_mask:0xf
	v_fmac_f32_dpp v178, v82, v212 row_shl:14 row_mask:0xf bank_mask:0xf
	v_fmac_f32_dpp v179, v83, v213 row_shl:14 row_mask:0xf bank_mask:0xf
	v_pk_mul_f32 v[180:181], v[166:167], v[172:173]
	v_pk_mul_f32 v[182:183], v[166:167], v[174:175]
	v_pk_mul_f32 v[180:181], v[172:173], v[180:181]
	v_pk_mul_f32 v[182:183], v[174:175], v[182:183]
	v_pk_fma_f32 v[180:181], v[172:173], v[180:181], v[172:173]
	v_pk_fma_f32 v[182:183], v[174:175], v[182:183], v[174:175]
	v_pk_mul_f32 v[180:181], v[250:251], v[180:181]
	v_pk_mul_f32 v[182:183], v[250:251], v[182:183]
	v_exp_f32_e32 v180, v180
	v_exp_f32_e32 v181, v181
	v_exp_f32_e32 v182, v182
	v_exp_f32_e32 v183, v183
	v_pk_add_f32 v[180:181], v[180:181], 1.0 op_sel_hi:[1,0]
	v_pk_add_f32 v[182:183], v[182:183], 1.0 op_sel_hi:[1,0]
	v_rcp_f32_e32 v180, v180
	v_rcp_f32_e32 v181, v181
	v_rcp_f32_e32 v182, v182
	v_rcp_f32_e32 v183, v183
	v_pk_mul_f32 v[172:173], v[172:173], v[180:181]
	v_pk_mul_f32 v[174:175], v[174:175], v[182:183]
	v_pk_mul_f32 v[172:173], v[172:173], v[176:177]
	v_pk_mul_f32 v[174:175], v[174:175], v[178:179]
	v_cvt_pk_bf16_f32 v84, v172, v173
	v_cvt_pk_bf16_f32 v85, v174, v175
	v_pk_fma_f32 v[172:173], v[202:203], v[100:101], v[206:207]
	v_pk_fma_f32 v[174:175], v[204:205], v[102:103], v[208:209]
	v_pk_fma_f32 v[176:177], v[218:219], v[80:81], v[222:223]
	v_pk_fma_f32 v[178:179], v[220:221], v[82:83], v[224:225]
	v_fmac_f32_dpp v172, v100, v198 row_shr:1 row_mask:0xf bank_mask:0xf
	v_fmac_f32_dpp v173, v101, v199 row_shr:1 row_mask:0xf bank_mask:0xf
	v_fmac_f32_dpp v174, v102, v200 row_shr:1 row_mask:0xf bank_mask:0xf
	v_fmac_f32_dpp v175, v103, v201 row_shr:1 row_mask:0xf bank_mask:0xf
	v_fmac_f32_dpp v176, v80, v214 row_shr:1 row_mask:0xf bank_mask:0xf
	v_fmac_f32_dpp v177, v81, v215 row_shr:1 row_mask:0xf bank_mask:0xf
	v_fmac_f32_dpp v178, v82, v216 row_shr:1 row_mask:0xf bank_mask:0xf
	v_fmac_f32_dpp v179, v83, v217 row_shr:1 row_mask:0xf bank_mask:0xf
	v_fmac_f32_dpp v172, v100, v194 row_shr:2 row_mask:0xf bank_mask:0xf
	v_fmac_f32_dpp v173, v101, v195 row_shr:2 row_mask:0xf bank_mask:0xf
	v_fmac_f32_dpp v174, v102, v196 row_shr:2 row_mask:0xf bank_mask:0xf
	v_fmac_f32_dpp v175, v103, v197 row_shr:2 row_mask:0xf bank_mask:0xf
	v_fmac_f32_dpp v176, v80, v210 row_shr:2 row_mask:0xf bank_mask:0xf
	v_fmac_f32_dpp v177, v81, v211 row_shr:2 row_mask:0xf bank_mask:0xf
	v_fmac_f32_dpp v178, v82, v212 row_shr:2 row_mask:0xf bank_mask:0xf
	v_fmac_f32_dpp v179, v83, v213 row_shr:2 row_mask:0xf bank_mask:0xf
	v_fmac_f32_dpp v172, v112, v198 row_shl:15 row_mask:0xf bank_mask:0xf
	v_fmac_f32_dpp v173, v113, v199 row_shl:15 row_mask:0xf bank_mask:0xf
	v_fmac_f32_dpp v174, v114, v200 row_shl:15 row_mask:0xf bank_mask:0xf
	v_fmac_f32_dpp v175, v115, v201 row_shl:15 row_mask:0xf bank_mask:0xf
	v_fmac_f32_dpp v176, v96, v214 row_shl:15 row_mask:0xf bank_mask:0xf
	v_fmac_f32_dpp v177, v97, v215 row_shl:15 row_mask:0xf bank_mask:0xf
	v_fmac_f32_dpp v178, v98, v216 row_shl:15 row_mask:0xf bank_mask:0xf
	v_fmac_f32_dpp v179, v99, v217 row_shl:15 row_mask:0xf bank_mask:0xf
	v_fmac_f32_dpp v172, v112, v194 row_shl:14 row_mask:0xf bank_mask:0xf
	v_fmac_f32_dpp v173, v113, v195 row_shl:14 row_mask:0xf bank_mask:0xf
	v_fmac_f32_dpp v174, v114, v196 row_shl:14 row_mask:0xf bank_mask:0xf
	v_fmac_f32_dpp v175, v115, v197 row_shl:14 row_mask:0xf bank_mask:0xf
	v_fmac_f32_dpp v176, v96, v210 row_shl:14 row_mask:0xf bank_mask:0xf
	v_fmac_f32_dpp v177, v97, v211 row_shl:14 row_mask:0xf bank_mask:0xf
	v_fmac_f32_dpp v178, v98, v212 row_shl:14 row_mask:0xf bank_mask:0xf
	v_fmac_f32_dpp v179, v99, v213 row_shl:14 row_mask:0xf bank_mask:0xf
	v_pk_mul_f32 v[180:181], v[166:167], v[172:173]
	v_pk_mul_f32 v[182:183], v[166:167], v[174:175]
	v_pk_mul_f32 v[180:181], v[172:173], v[180:181]
	v_pk_mul_f32 v[182:183], v[174:175], v[182:183]
	v_pk_fma_f32 v[180:181], v[172:173], v[180:181], v[172:173]
	v_pk_fma_f32 v[182:183], v[174:175], v[182:183], v[174:175]
	v_pk_mul_f32 v[180:181], v[250:251], v[180:181]
	v_pk_mul_f32 v[182:183], v[250:251], v[182:183]
	v_exp_f32_e32 v180, v180
	v_exp_f32_e32 v181, v181
	v_exp_f32_e32 v182, v182
	v_exp_f32_e32 v183, v183
	v_pk_add_f32 v[180:181], v[180:181], 1.0 op_sel_hi:[1,0]
	v_pk_add_f32 v[182:183], v[182:183], 1.0 op_sel_hi:[1,0]
	v_rcp_f32_e32 v180, v180
	v_rcp_f32_e32 v181, v181
	v_rcp_f32_e32 v182, v182
	v_rcp_f32_e32 v183, v183
	v_pk_mul_f32 v[172:173], v[172:173], v[180:181]
	v_pk_mul_f32 v[174:175], v[174:175], v[182:183]
	v_pk_mul_f32 v[172:173], v[172:173], v[176:177]
	v_pk_mul_f32 v[174:175], v[174:175], v[178:179]
	v_cvt_pk_bf16_f32 v100, v172, v173
	v_cvt_pk_bf16_f32 v101, v174, v175
	v_pk_fma_f32 v[172:173], v[202:203], v[112:113], v[206:207]
	v_pk_fma_f32 v[174:175], v[204:205], v[114:115], v[208:209]
	v_pk_fma_f32 v[176:177], v[218:219], v[96:97], v[222:223]
	v_pk_fma_f32 v[178:179], v[220:221], v[98:99], v[224:225]
	v_fmac_f32_dpp v172, v112, v198 row_shr:1 row_mask:0xf bank_mask:0xf
	v_fmac_f32_dpp v173, v113, v199 row_shr:1 row_mask:0xf bank_mask:0xf
	v_fmac_f32_dpp v174, v114, v200 row_shr:1 row_mask:0xf bank_mask:0xf
	v_fmac_f32_dpp v175, v115, v201 row_shr:1 row_mask:0xf bank_mask:0xf
	v_fmac_f32_dpp v176, v96, v214 row_shr:1 row_mask:0xf bank_mask:0xf
	v_fmac_f32_dpp v177, v97, v215 row_shr:1 row_mask:0xf bank_mask:0xf
	v_fmac_f32_dpp v178, v98, v216 row_shr:1 row_mask:0xf bank_mask:0xf
	v_fmac_f32_dpp v179, v99, v217 row_shr:1 row_mask:0xf bank_mask:0xf
	v_fmac_f32_dpp v172, v112, v194 row_shr:2 row_mask:0xf bank_mask:0xf
	v_fmac_f32_dpp v173, v113, v195 row_shr:2 row_mask:0xf bank_mask:0xf
	v_fmac_f32_dpp v174, v114, v196 row_shr:2 row_mask:0xf bank_mask:0xf
	v_fmac_f32_dpp v175, v115, v197 row_shr:2 row_mask:0xf bank_mask:0xf
	v_fmac_f32_dpp v176, v96, v210 row_shr:2 row_mask:0xf bank_mask:0xf
	v_fmac_f32_dpp v177, v97, v211 row_shr:2 row_mask:0xf bank_mask:0xf
	v_fmac_f32_dpp v178, v98, v212 row_shr:2 row_mask:0xf bank_mask:0xf
	v_fmac_f32_dpp v179, v99, v213 row_shr:2 row_mask:0xf bank_mask:0xf
	v_fmac_f32_dpp v172, v124, v198 row_shl:15 row_mask:0xf bank_mask:0xf
	v_fmac_f32_dpp v173, v125, v199 row_shl:15 row_mask:0xf bank_mask:0xf
	v_fmac_f32_dpp v174, v126, v200 row_shl:15 row_mask:0xf bank_mask:0xf
	v_fmac_f32_dpp v175, v127, v201 row_shl:15 row_mask:0xf bank_mask:0xf
	v_fmac_f32_dpp v176, v116, v214 row_shl:15 row_mask:0xf bank_mask:0xf
	v_fmac_f32_dpp v177, v117, v215 row_shl:15 row_mask:0xf bank_mask:0xf
	v_fmac_f32_dpp v178, v118, v216 row_shl:15 row_mask:0xf bank_mask:0xf
	v_fmac_f32_dpp v179, v119, v217 row_shl:15 row_mask:0xf bank_mask:0xf
	v_fmac_f32_dpp v172, v124, v194 row_shl:14 row_mask:0xf bank_mask:0xf
	v_fmac_f32_dpp v173, v125, v195 row_shl:14 row_mask:0xf bank_mask:0xf
	v_fmac_f32_dpp v174, v126, v196 row_shl:14 row_mask:0xf bank_mask:0xf
	v_fmac_f32_dpp v175, v127, v197 row_shl:14 row_mask:0xf bank_mask:0xf
	v_fmac_f32_dpp v176, v116, v210 row_shl:14 row_mask:0xf bank_mask:0xf
	v_fmac_f32_dpp v177, v117, v211 row_shl:14 row_mask:0xf bank_mask:0xf
	v_fmac_f32_dpp v178, v118, v212 row_shl:14 row_mask:0xf bank_mask:0xf
	v_fmac_f32_dpp v179, v119, v213 row_shl:14 row_mask:0xf bank_mask:0xf
	v_pk_mul_f32 v[180:181], v[166:167], v[172:173]
	v_pk_mul_f32 v[182:183], v[166:167], v[174:175]
	v_pk_mul_f32 v[180:181], v[172:173], v[180:181]
	v_pk_mul_f32 v[182:183], v[174:175], v[182:183]
	v_pk_fma_f32 v[180:181], v[172:173], v[180:181], v[172:173]
	v_pk_fma_f32 v[182:183], v[174:175], v[182:183], v[174:175]
	v_pk_mul_f32 v[180:181], v[250:251], v[180:181]
	v_pk_mul_f32 v[182:183], v[250:251], v[182:183]
	v_exp_f32_e32 v180, v180
	v_exp_f32_e32 v181, v181
	v_exp_f32_e32 v182, v182
	v_exp_f32_e32 v183, v183
	v_pk_add_f32 v[180:181], v[180:181], 1.0 op_sel_hi:[1,0]
	v_pk_add_f32 v[182:183], v[182:183], 1.0 op_sel_hi:[1,0]
	v_rcp_f32_e32 v180, v180
	v_rcp_f32_e32 v181, v181
	v_rcp_f32_e32 v182, v182
	v_rcp_f32_e32 v183, v183
	v_pk_mul_f32 v[172:173], v[172:173], v[180:181]
	v_pk_mul_f32 v[174:175], v[174:175], v[182:183]
	v_pk_mul_f32 v[172:173], v[172:173], v[176:177]
	v_pk_mul_f32 v[174:175], v[174:175], v[178:179]
	v_cvt_pk_bf16_f32 v112, v172, v173
	v_cvt_pk_bf16_f32 v113, v174, v175
	v_pk_fma_f32 v[172:173], v[202:203], v[124:125], v[206:207]
	v_pk_fma_f32 v[174:175], v[204:205], v[126:127], v[208:209]
	v_pk_fma_f32 v[176:177], v[218:219], v[116:117], v[222:223]
	v_pk_fma_f32 v[178:179], v[220:221], v[118:119], v[224:225]
	v_fmac_f32_dpp v172, v124, v198 row_shr:1 row_mask:0xf bank_mask:0xf
	v_fmac_f32_dpp v173, v125, v199 row_shr:1 row_mask:0xf bank_mask:0xf
	v_fmac_f32_dpp v174, v126, v200 row_shr:1 row_mask:0xf bank_mask:0xf
	v_fmac_f32_dpp v175, v127, v201 row_shr:1 row_mask:0xf bank_mask:0xf
	v_fmac_f32_dpp v176, v116, v214 row_shr:1 row_mask:0xf bank_mask:0xf
	v_fmac_f32_dpp v177, v117, v215 row_shr:1 row_mask:0xf bank_mask:0xf
	v_fmac_f32_dpp v178, v118, v216 row_shr:1 row_mask:0xf bank_mask:0xf
	v_fmac_f32_dpp v179, v119, v217 row_shr:1 row_mask:0xf bank_mask:0xf
	v_fmac_f32_dpp v172, v124, v194 row_shr:2 row_mask:0xf bank_mask:0xf
	v_fmac_f32_dpp v173, v125, v195 row_shr:2 row_mask:0xf bank_mask:0xf
	v_fmac_f32_dpp v174, v126, v196 row_shr:2 row_mask:0xf bank_mask:0xf
	v_fmac_f32_dpp v175, v127, v197 row_shr:2 row_mask:0xf bank_mask:0xf
	v_fmac_f32_dpp v176, v116, v210 row_shr:2 row_mask:0xf bank_mask:0xf
	v_fmac_f32_dpp v177, v117, v211 row_shr:2 row_mask:0xf bank_mask:0xf
	v_fmac_f32_dpp v178, v118, v212 row_shr:2 row_mask:0xf bank_mask:0xf
	v_fmac_f32_dpp v179, v119, v213 row_shr:2 row_mask:0xf bank_mask:0xf
	v_fmac_f32_dpp v172, v128, v198 row_shl:15 row_mask:0xf bank_mask:0xf
	v_fmac_f32_dpp v173, v129, v199 row_shl:15 row_mask:0xf bank_mask:0xf
	v_fmac_f32_dpp v174, v130, v200 row_shl:15 row_mask:0xf bank_mask:0xf
	v_fmac_f32_dpp v175, v131, v201 row_shl:15 row_mask:0xf bank_mask:0xf
	v_fmac_f32_dpp v176, v132, v214 row_shl:15 row_mask:0xf bank_mask:0xf
	v_fmac_f32_dpp v177, v133, v215 row_shl:15 row_mask:0xf bank_mask:0xf
	v_fmac_f32_dpp v178, v134, v216 row_shl:15 row_mask:0xf bank_mask:0xf
	v_fmac_f32_dpp v179, v135, v217 row_shl:15 row_mask:0xf bank_mask:0xf
	v_fmac_f32_dpp v172, v128, v194 row_shl:14 row_mask:0xf bank_mask:0xf
	v_fmac_f32_dpp v173, v129, v195 row_shl:14 row_mask:0xf bank_mask:0xf
	v_fmac_f32_dpp v174, v130, v196 row_shl:14 row_mask:0xf bank_mask:0xf
	v_fmac_f32_dpp v175, v131, v197 row_shl:14 row_mask:0xf bank_mask:0xf
	v_fmac_f32_dpp v176, v132, v210 row_shl:14 row_mask:0xf bank_mask:0xf
	v_fmac_f32_dpp v177, v133, v211 row_shl:14 row_mask:0xf bank_mask:0xf
	v_fmac_f32_dpp v178, v134, v212 row_shl:14 row_mask:0xf bank_mask:0xf
	v_fmac_f32_dpp v179, v135, v213 row_shl:14 row_mask:0xf bank_mask:0xf
	v_pk_mul_f32 v[180:181], v[166:167], v[172:173]
	v_pk_mul_f32 v[182:183], v[166:167], v[174:175]
	v_pk_mul_f32 v[180:181], v[172:173], v[180:181]
	v_pk_mul_f32 v[182:183], v[174:175], v[182:183]
	v_pk_fma_f32 v[180:181], v[172:173], v[180:181], v[172:173]
	v_pk_fma_f32 v[182:183], v[174:175], v[182:183], v[174:175]
	v_pk_mul_f32 v[180:181], v[250:251], v[180:181]
	v_pk_mul_f32 v[182:183], v[250:251], v[182:183]
	v_exp_f32_e32 v180, v180
	v_exp_f32_e32 v181, v181
	v_exp_f32_e32 v182, v182
	v_exp_f32_e32 v183, v183
	v_pk_add_f32 v[180:181], v[180:181], 1.0 op_sel_hi:[1,0]
	v_pk_add_f32 v[182:183], v[182:183], 1.0 op_sel_hi:[1,0]
	v_rcp_f32_e32 v180, v180
	v_rcp_f32_e32 v181, v181
	v_rcp_f32_e32 v182, v182
	v_rcp_f32_e32 v183, v183
	v_pk_mul_f32 v[172:173], v[172:173], v[180:181]
	v_pk_mul_f32 v[174:175], v[174:175], v[182:183]
	v_pk_mul_f32 v[172:173], v[172:173], v[176:177]
	v_pk_mul_f32 v[174:175], v[174:175], v[178:179]
	v_cvt_pk_bf16_f32 v124, v172, v173
	v_cvt_pk_bf16_f32 v125, v174, v175
	v_pk_fma_f32 v[172:173], v[202:203], v[20:21], v[206:207]
	v_pk_fma_f32 v[174:175], v[204:205], v[22:23], v[208:209]
	v_pk_fma_f32 v[176:177], v[218:219], v[4:5], v[222:223]
	v_pk_fma_f32 v[178:179], v[220:221], v[6:7], v[224:225]
	v_fmac_f32_dpp v172, v20, v198 row_shr:1 row_mask:0xf bank_mask:0xf
	v_fmac_f32_dpp v173, v21, v199 row_shr:1 row_mask:0xf bank_mask:0xf
	v_fmac_f32_dpp v174, v22, v200 row_shr:1 row_mask:0xf bank_mask:0xf
	v_fmac_f32_dpp v175, v23, v201 row_shr:1 row_mask:0xf bank_mask:0xf
	v_fmac_f32_dpp v176, v4, v214 row_shr:1 row_mask:0xf bank_mask:0xf
	v_fmac_f32_dpp v177, v5, v215 row_shr:1 row_mask:0xf bank_mask:0xf
	v_fmac_f32_dpp v178, v6, v216 row_shr:1 row_mask:0xf bank_mask:0xf
	v_fmac_f32_dpp v179, v7, v217 row_shr:1 row_mask:0xf bank_mask:0xf
	v_fmac_f32_dpp v172, v20, v194 row_shr:2 row_mask:0xf bank_mask:0xf
	v_fmac_f32_dpp v173, v21, v195 row_shr:2 row_mask:0xf bank_mask:0xf
	v_fmac_f32_dpp v174, v22, v196 row_shr:2 row_mask:0xf bank_mask:0xf
	v_fmac_f32_dpp v175, v23, v197 row_shr:2 row_mask:0xf bank_mask:0xf
	v_fmac_f32_dpp v176, v4, v210 row_shr:2 row_mask:0xf bank_mask:0xf
	v_fmac_f32_dpp v177, v5, v211 row_shr:2 row_mask:0xf bank_mask:0xf
	v_fmac_f32_dpp v178, v6, v212 row_shr:2 row_mask:0xf bank_mask:0xf
	v_fmac_f32_dpp v179, v7, v213 row_shr:2 row_mask:0xf bank_mask:0xf
	v_fmac_f32_dpp v172, v36, v198 row_shl:15 row_mask:0xf bank_mask:0xf
	v_fmac_f32_dpp v173, v37, v199 row_shl:15 row_mask:0xf bank_mask:0xf
	v_fmac_f32_dpp v174, v38, v200 row_shl:15 row_mask:0xf bank_mask:0xf
	v_fmac_f32_dpp v175, v39, v201 row_shl:15 row_mask:0xf bank_mask:0xf
	v_fmac_f32_dpp v176, v16, v214 row_shl:15 row_mask:0xf bank_mask:0xf
	v_fmac_f32_dpp v177, v17, v215 row_shl:15 row_mask:0xf bank_mask:0xf
	v_fmac_f32_dpp v178, v18, v216 row_shl:15 row_mask:0xf bank_mask:0xf
	v_fmac_f32_dpp v179, v19, v217 row_shl:15 row_mask:0xf bank_mask:0xf
	v_fmac_f32_dpp v172, v36, v194 row_shl:14 row_mask:0xf bank_mask:0xf
	v_fmac_f32_dpp v173, v37, v195 row_shl:14 row_mask:0xf bank_mask:0xf
	v_fmac_f32_dpp v174, v38, v196 row_shl:14 row_mask:0xf bank_mask:0xf
	v_fmac_f32_dpp v175, v39, v197 row_shl:14 row_mask:0xf bank_mask:0xf
	v_fmac_f32_dpp v176, v16, v210 row_shl:14 row_mask:0xf bank_mask:0xf
	v_fmac_f32_dpp v177, v17, v211 row_shl:14 row_mask:0xf bank_mask:0xf
	v_fmac_f32_dpp v178, v18, v212 row_shl:14 row_mask:0xf bank_mask:0xf
	v_fmac_f32_dpp v179, v19, v213 row_shl:14 row_mask:0xf bank_mask:0xf
	v_pk_mul_f32 v[180:181], v[166:167], v[172:173]
	v_pk_mul_f32 v[182:183], v[166:167], v[174:175]
	v_pk_mul_f32 v[180:181], v[172:173], v[180:181]
	v_pk_mul_f32 v[182:183], v[174:175], v[182:183]
	v_pk_fma_f32 v[180:181], v[172:173], v[180:181], v[172:173]
	v_pk_fma_f32 v[182:183], v[174:175], v[182:183], v[174:175]
	v_pk_mul_f32 v[180:181], v[250:251], v[180:181]
	v_pk_mul_f32 v[182:183], v[250:251], v[182:183]
	v_exp_f32_e32 v180, v180
	v_exp_f32_e32 v181, v181
	v_exp_f32_e32 v182, v182
	v_exp_f32_e32 v183, v183
	v_pk_add_f32 v[180:181], v[180:181], 1.0 op_sel_hi:[1,0]
	v_pk_add_f32 v[182:183], v[182:183], 1.0 op_sel_hi:[1,0]
	v_rcp_f32_e32 v180, v180
	v_rcp_f32_e32 v181, v181
	v_rcp_f32_e32 v182, v182
	v_rcp_f32_e32 v183, v183
	v_pk_mul_f32 v[172:173], v[172:173], v[180:181]
	v_pk_mul_f32 v[174:175], v[174:175], v[182:183]
	v_pk_mul_f32 v[172:173], v[172:173], v[176:177]
	v_pk_mul_f32 v[174:175], v[174:175], v[178:179]
	v_cvt_pk_bf16_f32 v20, v172, v173
	v_cvt_pk_bf16_f32 v21, v174, v175
	v_pk_fma_f32 v[172:173], v[202:203], v[36:37], v[206:207]
	v_pk_fma_f32 v[174:175], v[204:205], v[38:39], v[208:209]
	v_pk_fma_f32 v[176:177], v[218:219], v[16:17], v[222:223]
	v_pk_fma_f32 v[178:179], v[220:221], v[18:19], v[224:225]
	v_fmac_f32_dpp v172, v36, v198 row_shr:1 row_mask:0xf bank_mask:0xf
	v_fmac_f32_dpp v173, v37, v199 row_shr:1 row_mask:0xf bank_mask:0xf
	v_fmac_f32_dpp v174, v38, v200 row_shr:1 row_mask:0xf bank_mask:0xf
	v_fmac_f32_dpp v175, v39, v201 row_shr:1 row_mask:0xf bank_mask:0xf
	v_fmac_f32_dpp v176, v16, v214 row_shr:1 row_mask:0xf bank_mask:0xf
	v_fmac_f32_dpp v177, v17, v215 row_shr:1 row_mask:0xf bank_mask:0xf
	v_fmac_f32_dpp v178, v18, v216 row_shr:1 row_mask:0xf bank_mask:0xf
	v_fmac_f32_dpp v179, v19, v217 row_shr:1 row_mask:0xf bank_mask:0xf
	v_fmac_f32_dpp v172, v36, v194 row_shr:2 row_mask:0xf bank_mask:0xf
	v_fmac_f32_dpp v173, v37, v195 row_shr:2 row_mask:0xf bank_mask:0xf
	v_fmac_f32_dpp v174, v38, v196 row_shr:2 row_mask:0xf bank_mask:0xf
	v_fmac_f32_dpp v175, v39, v197 row_shr:2 row_mask:0xf bank_mask:0xf
	v_fmac_f32_dpp v176, v16, v210 row_shr:2 row_mask:0xf bank_mask:0xf
	v_fmac_f32_dpp v177, v17, v211 row_shr:2 row_mask:0xf bank_mask:0xf
	v_fmac_f32_dpp v178, v18, v212 row_shr:2 row_mask:0xf bank_mask:0xf
	v_fmac_f32_dpp v179, v19, v213 row_shr:2 row_mask:0xf bank_mask:0xf
	v_fmac_f32_dpp v172, v52, v198 row_shl:15 row_mask:0xf bank_mask:0xf
	v_fmac_f32_dpp v173, v53, v199 row_shl:15 row_mask:0xf bank_mask:0xf
	v_fmac_f32_dpp v174, v54, v200 row_shl:15 row_mask:0xf bank_mask:0xf
	v_fmac_f32_dpp v175, v55, v201 row_shl:15 row_mask:0xf bank_mask:0xf
	v_fmac_f32_dpp v176, v32, v214 row_shl:15 row_mask:0xf bank_mask:0xf
	v_fmac_f32_dpp v177, v33, v215 row_shl:15 row_mask:0xf bank_mask:0xf
	v_fmac_f32_dpp v178, v34, v216 row_shl:15 row_mask:0xf bank_mask:0xf
	v_fmac_f32_dpp v179, v35, v217 row_shl:15 row_mask:0xf bank_mask:0xf
	v_fmac_f32_dpp v172, v52, v194 row_shl:14 row_mask:0xf bank_mask:0xf
	v_fmac_f32_dpp v173, v53, v195 row_shl:14 row_mask:0xf bank_mask:0xf
	v_fmac_f32_dpp v174, v54, v196 row_shl:14 row_mask:0xf bank_mask:0xf
	v_fmac_f32_dpp v175, v55, v197 row_shl:14 row_mask:0xf bank_mask:0xf
	v_fmac_f32_dpp v176, v32, v210 row_shl:14 row_mask:0xf bank_mask:0xf
	v_fmac_f32_dpp v177, v33, v211 row_shl:14 row_mask:0xf bank_mask:0xf
	v_fmac_f32_dpp v178, v34, v212 row_shl:14 row_mask:0xf bank_mask:0xf
	v_fmac_f32_dpp v179, v35, v213 row_shl:14 row_mask:0xf bank_mask:0xf
	v_pk_mul_f32 v[180:181], v[166:167], v[172:173]
	v_pk_mul_f32 v[182:183], v[166:167], v[174:175]
	v_pk_mul_f32 v[180:181], v[172:173], v[180:181]
	v_pk_mul_f32 v[182:183], v[174:175], v[182:183]
	v_pk_fma_f32 v[180:181], v[172:173], v[180:181], v[172:173]
	v_pk_fma_f32 v[182:183], v[174:175], v[182:183], v[174:175]
	v_pk_mul_f32 v[180:181], v[250:251], v[180:181]
	v_pk_mul_f32 v[182:183], v[250:251], v[182:183]
	v_exp_f32_e32 v180, v180
	v_exp_f32_e32 v181, v181
	v_exp_f32_e32 v182, v182
	v_exp_f32_e32 v183, v183
	v_pk_add_f32 v[180:181], v[180:181], 1.0 op_sel_hi:[1,0]
	v_pk_add_f32 v[182:183], v[182:183], 1.0 op_sel_hi:[1,0]
	v_rcp_f32_e32 v180, v180
	v_rcp_f32_e32 v181, v181
	v_rcp_f32_e32 v182, v182
	v_rcp_f32_e32 v183, v183
	v_pk_mul_f32 v[172:173], v[172:173], v[180:181]
	v_pk_mul_f32 v[174:175], v[174:175], v[182:183]
	v_pk_mul_f32 v[172:173], v[172:173], v[176:177]
	v_pk_mul_f32 v[174:175], v[174:175], v[178:179]
	v_cvt_pk_bf16_f32 v36, v172, v173
	v_cvt_pk_bf16_f32 v37, v174, v175
	v_pk_fma_f32 v[172:173], v[202:203], v[52:53], v[206:207]
	v_pk_fma_f32 v[174:175], v[204:205], v[54:55], v[208:209]
	v_pk_fma_f32 v[176:177], v[218:219], v[32:33], v[222:223]
	v_pk_fma_f32 v[178:179], v[220:221], v[34:35], v[224:225]
	v_fmac_f32_dpp v172, v52, v198 row_shr:1 row_mask:0xf bank_mask:0xf
	v_fmac_f32_dpp v173, v53, v199 row_shr:1 row_mask:0xf bank_mask:0xf
	v_fmac_f32_dpp v174, v54, v200 row_shr:1 row_mask:0xf bank_mask:0xf
	v_fmac_f32_dpp v175, v55, v201 row_shr:1 row_mask:0xf bank_mask:0xf
	v_fmac_f32_dpp v176, v32, v214 row_shr:1 row_mask:0xf bank_mask:0xf
	v_fmac_f32_dpp v177, v33, v215 row_shr:1 row_mask:0xf bank_mask:0xf
	v_fmac_f32_dpp v178, v34, v216 row_shr:1 row_mask:0xf bank_mask:0xf
	v_fmac_f32_dpp v179, v35, v217 row_shr:1 row_mask:0xf bank_mask:0xf
	v_fmac_f32_dpp v172, v52, v194 row_shr:2 row_mask:0xf bank_mask:0xf
	v_fmac_f32_dpp v173, v53, v195 row_shr:2 row_mask:0xf bank_mask:0xf
	v_fmac_f32_dpp v174, v54, v196 row_shr:2 row_mask:0xf bank_mask:0xf
	v_fmac_f32_dpp v175, v55, v197 row_shr:2 row_mask:0xf bank_mask:0xf
	v_fmac_f32_dpp v176, v32, v210 row_shr:2 row_mask:0xf bank_mask:0xf
	v_fmac_f32_dpp v177, v33, v211 row_shr:2 row_mask:0xf bank_mask:0xf
	v_fmac_f32_dpp v178, v34, v212 row_shr:2 row_mask:0xf bank_mask:0xf
	v_fmac_f32_dpp v179, v35, v213 row_shr:2 row_mask:0xf bank_mask:0xf
	v_fmac_f32_dpp v172, v60, v198 row_shl:15 row_mask:0xf bank_mask:0xf
	v_fmac_f32_dpp v173, v61, v199 row_shl:15 row_mask:0xf bank_mask:0xf
	v_fmac_f32_dpp v174, v62, v200 row_shl:15 row_mask:0xf bank_mask:0xf
	v_fmac_f32_dpp v175, v63, v201 row_shl:15 row_mask:0xf bank_mask:0xf
	v_fmac_f32_dpp v176, v48, v214 row_shl:15 row_mask:0xf bank_mask:0xf
	v_fmac_f32_dpp v177, v49, v215 row_shl:15 row_mask:0xf bank_mask:0xf
	v_fmac_f32_dpp v178, v50, v216 row_shl:15 row_mask:0xf bank_mask:0xf
	v_fmac_f32_dpp v179, v51, v217 row_shl:15 row_mask:0xf bank_mask:0xf
	v_fmac_f32_dpp v172, v60, v194 row_shl:14 row_mask:0xf bank_mask:0xf
	v_fmac_f32_dpp v173, v61, v195 row_shl:14 row_mask:0xf bank_mask:0xf
	v_fmac_f32_dpp v174, v62, v196 row_shl:14 row_mask:0xf bank_mask:0xf
	v_fmac_f32_dpp v175, v63, v197 row_shl:14 row_mask:0xf bank_mask:0xf
	v_fmac_f32_dpp v176, v48, v210 row_shl:14 row_mask:0xf bank_mask:0xf
	v_fmac_f32_dpp v177, v49, v211 row_shl:14 row_mask:0xf bank_mask:0xf
	v_fmac_f32_dpp v178, v50, v212 row_shl:14 row_mask:0xf bank_mask:0xf
	v_fmac_f32_dpp v179, v51, v213 row_shl:14 row_mask:0xf bank_mask:0xf
	v_pk_mul_f32 v[180:181], v[166:167], v[172:173]
	v_pk_mul_f32 v[182:183], v[166:167], v[174:175]
	v_pk_mul_f32 v[180:181], v[172:173], v[180:181]
	v_pk_mul_f32 v[182:183], v[174:175], v[182:183]
	v_pk_fma_f32 v[180:181], v[172:173], v[180:181], v[172:173]
	v_pk_fma_f32 v[182:183], v[174:175], v[182:183], v[174:175]
	v_pk_mul_f32 v[180:181], v[250:251], v[180:181]
	v_pk_mul_f32 v[182:183], v[250:251], v[182:183]
	v_exp_f32_e32 v180, v180
	v_exp_f32_e32 v181, v181
	v_exp_f32_e32 v182, v182
	v_exp_f32_e32 v183, v183
	v_pk_add_f32 v[180:181], v[180:181], 1.0 op_sel_hi:[1,0]
	v_pk_add_f32 v[182:183], v[182:183], 1.0 op_sel_hi:[1,0]
	v_rcp_f32_e32 v180, v180
	v_rcp_f32_e32 v181, v181
	v_rcp_f32_e32 v182, v182
	v_rcp_f32_e32 v183, v183
	v_pk_mul_f32 v[172:173], v[172:173], v[180:181]
	v_pk_mul_f32 v[174:175], v[174:175], v[182:183]
	v_pk_mul_f32 v[172:173], v[172:173], v[176:177]
	v_pk_mul_f32 v[174:175], v[174:175], v[178:179]
	v_cvt_pk_bf16_f32 v52, v172, v173
	v_cvt_pk_bf16_f32 v53, v174, v175
	v_pk_fma_f32 v[172:173], v[202:203], v[60:61], v[206:207]
	v_pk_fma_f32 v[174:175], v[204:205], v[62:63], v[208:209]
	v_pk_fma_f32 v[176:177], v[218:219], v[48:49], v[222:223]
	v_pk_fma_f32 v[178:179], v[220:221], v[50:51], v[224:225]
	v_fmac_f32_dpp v172, v60, v198 row_shr:1 row_mask:0xf bank_mask:0xf
	v_fmac_f32_dpp v173, v61, v199 row_shr:1 row_mask:0xf bank_mask:0xf
	v_fmac_f32_dpp v174, v62, v200 row_shr:1 row_mask:0xf bank_mask:0xf
	v_fmac_f32_dpp v175, v63, v201 row_shr:1 row_mask:0xf bank_mask:0xf
	v_fmac_f32_dpp v176, v48, v214 row_shr:1 row_mask:0xf bank_mask:0xf
	v_fmac_f32_dpp v177, v49, v215 row_shr:1 row_mask:0xf bank_mask:0xf
	v_fmac_f32_dpp v178, v50, v216 row_shr:1 row_mask:0xf bank_mask:0xf
	v_fmac_f32_dpp v179, v51, v217 row_shr:1 row_mask:0xf bank_mask:0xf
	v_fmac_f32_dpp v172, v60, v194 row_shr:2 row_mask:0xf bank_mask:0xf
	v_fmac_f32_dpp v173, v61, v195 row_shr:2 row_mask:0xf bank_mask:0xf
	v_fmac_f32_dpp v174, v62, v196 row_shr:2 row_mask:0xf bank_mask:0xf
	v_fmac_f32_dpp v175, v63, v197 row_shr:2 row_mask:0xf bank_mask:0xf
	v_fmac_f32_dpp v176, v48, v210 row_shr:2 row_mask:0xf bank_mask:0xf
	v_fmac_f32_dpp v177, v49, v211 row_shr:2 row_mask:0xf bank_mask:0xf
	v_fmac_f32_dpp v178, v50, v212 row_shr:2 row_mask:0xf bank_mask:0xf
	v_fmac_f32_dpp v179, v51, v213 row_shr:2 row_mask:0xf bank_mask:0xf
	v_fmac_f32_dpp v172, v136, v198 row_shl:15 row_mask:0xf bank_mask:0xf
	v_fmac_f32_dpp v173, v137, v199 row_shl:15 row_mask:0xf bank_mask:0xf
	v_fmac_f32_dpp v174, v138, v200 row_shl:15 row_mask:0xf bank_mask:0xf
	v_fmac_f32_dpp v175, v139, v201 row_shl:15 row_mask:0xf bank_mask:0xf
	v_fmac_f32_dpp v176, v140, v214 row_shl:15 row_mask:0xf bank_mask:0xf
	v_fmac_f32_dpp v177, v141, v215 row_shl:15 row_mask:0xf bank_mask:0xf
	v_fmac_f32_dpp v178, v142, v216 row_shl:15 row_mask:0xf bank_mask:0xf
	v_fmac_f32_dpp v179, v143, v217 row_shl:15 row_mask:0xf bank_mask:0xf
	v_fmac_f32_dpp v172, v136, v194 row_shl:14 row_mask:0xf bank_mask:0xf
	v_fmac_f32_dpp v173, v137, v195 row_shl:14 row_mask:0xf bank_mask:0xf
	v_fmac_f32_dpp v174, v138, v196 row_shl:14 row_mask:0xf bank_mask:0xf
	v_fmac_f32_dpp v175, v139, v197 row_shl:14 row_mask:0xf bank_mask:0xf
	v_fmac_f32_dpp v176, v140, v210 row_shl:14 row_mask:0xf bank_mask:0xf
	v_fmac_f32_dpp v177, v141, v211 row_shl:14 row_mask:0xf bank_mask:0xf
	v_fmac_f32_dpp v178, v142, v212 row_shl:14 row_mask:0xf bank_mask:0xf
	v_fmac_f32_dpp v179, v143, v213 row_shl:14 row_mask:0xf bank_mask:0xf
	v_pk_mul_f32 v[180:181], v[166:167], v[172:173]
	v_pk_mul_f32 v[182:183], v[166:167], v[174:175]
	v_pk_mul_f32 v[180:181], v[172:173], v[180:181]
	v_pk_mul_f32 v[182:183], v[174:175], v[182:183]
	v_pk_fma_f32 v[180:181], v[172:173], v[180:181], v[172:173]
	v_pk_fma_f32 v[182:183], v[174:175], v[182:183], v[174:175]
	v_pk_mul_f32 v[180:181], v[250:251], v[180:181]
	v_pk_mul_f32 v[182:183], v[250:251], v[182:183]
	v_exp_f32_e32 v180, v180
	v_exp_f32_e32 v181, v181
	v_exp_f32_e32 v182, v182
	v_exp_f32_e32 v183, v183
	v_pk_add_f32 v[180:181], v[180:181], 1.0 op_sel_hi:[1,0]
	v_pk_add_f32 v[182:183], v[182:183], 1.0 op_sel_hi:[1,0]
	v_rcp_f32_e32 v180, v180
	v_rcp_f32_e32 v181, v181
	v_rcp_f32_e32 v182, v182
	v_rcp_f32_e32 v183, v183
	v_pk_mul_f32 v[172:173], v[172:173], v[180:181]
	v_pk_mul_f32 v[174:175], v[174:175], v[182:183]
	v_pk_mul_f32 v[172:173], v[172:173], v[176:177]
	v_pk_mul_f32 v[174:175], v[174:175], v[178:179]
	v_cvt_pk_bf16_f32 v60, v172, v173
	v_cvt_pk_bf16_f32 v61, v174, v175
	ds_read_b128 v[226:229], v152 offset:16
	ds_read_b128 v[230:233], v152 offset:528
	ds_read_b128 v[206:209], v152 offset:1040
	ds_read_b128 v[222:225], v152 offset:1552
	ds_read_b128 v[194:197], v152 offset:2064
	ds_read_b128 v[198:201], v152 offset:2576
	ds_read_b128 v[202:205], v152 offset:3088
	ds_read_b128 v[210:213], v152 offset:3600
	ds_read_b128 v[214:217], v152 offset:4112
	ds_read_b128 v[218:221], v152 offset:4624
	ds_read_b128 v[128:131], v238 offset:16
	ds_read_b128 v[132:135], v238 offset:48
	ds_read_b128 v[136:139], v239 offset:16
	ds_read_b128 v[140:143], v239 offset:48
	s_waitcnt lgkmcnt(0)
	s_cmp_lg_u32 s33, 0
	s_cbranch_scc1 .Lepi9_wr1_2
	s_mov_b64 exec, s[52:53]
	v_add_f32_e32 v184, v120, v226
	v_add_f32_e32 v185, v121, v227
	v_add_f32_e32 v186, v122, v228
	v_add_f32_e32 v187, v123, v229
	v_cvt_pk_bf16_f32 v184, v184, v185
	v_cvt_pk_bf16_f32 v185, v186, v187
	global_store_dwordx2 v236, v[184:185], s[58:59] offset:8
	v_add_f32_e32 v188, v104, v230
	v_add_f32_e32 v189, v105, v231
	v_add_f32_e32 v190, v106, v232
	v_add_f32_e32 v191, v107, v233
	v_cvt_pk_bf16_f32 v188, v188, v189
	v_cvt_pk_bf16_f32 v189, v190, v191
	v_add_u32_e32 v241, 0x1600, v236
	global_store_dwordx2 v241, v[188:189], s[58:59] offset:8
	s_mov_b64 exec, -1
	s_branch .Lepi9_wrend_2

.Lepi9_wrend_2:
	v_add_f32_e32 v180, v194, v198
	v_add_f32_e32 v181, v195, v199
	v_add_f32_e32 v182, v196, v200
	v_add_f32_e32 v183, v197, v201
	v_add_f32_e32 v180, v180, v202
	v_add_f32_e32 v181, v181, v203
	v_add_f32_e32 v182, v182, v204
	v_add_f32_e32 v183, v183, v205
	v_fma_f32 v206, v226, v180, v206
	v_fma_f32 v207, v227, v181, v207
	v_fma_f32 v208, v228, v182, v208
	v_fma_f32 v209, v229, v183, v209
	v_add_f32_e32 v180, v210, v214
	v_add_f32_e32 v181, v211, v215
	v_add_f32_e32 v182, v212, v216
	v_add_f32_e32 v183, v213, v217
	v_add_f32_e32 v180, v180, v218
	v_add_f32_e32 v181, v181, v219
	v_add_f32_e32 v182, v182, v220
	v_add_f32_e32 v183, v183, v221
	v_fma_f32 v222, v230, v180, v222
	v_fma_f32 v223, v231, v181, v223
	v_fma_f32 v224, v232, v182, v224
	v_fma_f32 v225, v233, v183, v225
	s_waitcnt lgkmcnt(0)
	v_pk_fma_f32 v[172:173], v[202:203], v[76:77], v[206:207]
	v_pk_fma_f32 v[174:175], v[204:205], v[78:79], v[208:209]
	v_pk_fma_f32 v[176:177], v[218:219], v[64:65], v[222:223]
	v_pk_fma_f32 v[178:179], v[220:221], v[66:67], v[224:225]
	v_fmac_f32_dpp v172, v76, v198 row_shr:1 row_mask:0xf bank_mask:0xf
	v_fmac_f32_dpp v173, v77, v199 row_shr:1 row_mask:0xf bank_mask:0xf
	v_fmac_f32_dpp v174, v78, v200 row_shr:1 row_mask:0xf bank_mask:0xf
	v_fmac_f32_dpp v175, v79, v201 row_shr:1 row_mask:0xf bank_mask:0xf
	v_fmac_f32_dpp v176, v64, v214 row_shr:1 row_mask:0xf bank_mask:0xf
	v_fmac_f32_dpp v177, v65, v215 row_shr:1 row_mask:0xf bank_mask:0xf
	v_fmac_f32_dpp v178, v66, v216 row_shr:1 row_mask:0xf bank_mask:0xf
	v_fmac_f32_dpp v179, v67, v217 row_shr:1 row_mask:0xf bank_mask:0xf
	v_fmac_f32_dpp v172, v76, v194 row_shr:2 row_mask:0xf bank_mask:0xf
	v_fmac_f32_dpp v173, v77, v195 row_shr:2 row_mask:0xf bank_mask:0xf
	v_fmac_f32_dpp v174, v78, v196 row_shr:2 row_mask:0xf bank_mask:0xf
	v_fmac_f32_dpp v175, v79, v197 row_shr:2 row_mask:0xf bank_mask:0xf
	v_fmac_f32_dpp v176, v64, v210 row_shr:2 row_mask:0xf bank_mask:0xf
	v_fmac_f32_dpp v177, v65, v211 row_shr:2 row_mask:0xf bank_mask:0xf
	v_fmac_f32_dpp v178, v66, v212 row_shr:2 row_mask:0xf bank_mask:0xf
	v_fmac_f32_dpp v179, v67, v213 row_shr:2 row_mask:0xf bank_mask:0xf
	v_fmac_f32_dpp v172, v92, v198 row_shl:15 row_mask:0xf bank_mask:0xf
	v_fmac_f32_dpp v173, v93, v199 row_shl:15 row_mask:0xf bank_mask:0xf
	v_fmac_f32_dpp v174, v94, v200 row_shl:15 row_mask:0xf bank_mask:0xf
	v_fmac_f32_dpp v175, v95, v201 row_shl:15 row_mask:0xf bank_mask:0xf
	v_fmac_f32_dpp v176, v72, v214 row_shl:15 row_mask:0xf bank_mask:0xf
	v_fmac_f32_dpp v177, v73, v215 row_shl:15 row_mask:0xf bank_mask:0xf
	v_fmac_f32_dpp v178, v74, v216 row_shl:15 row_mask:0xf bank_mask:0xf
	v_fmac_f32_dpp v179, v75, v217 row_shl:15 row_mask:0xf bank_mask:0xf
	v_fmac_f32_dpp v172, v92, v194 row_shl:14 row_mask:0xf bank_mask:0xf
	v_fmac_f32_dpp v173, v93, v195 row_shl:14 row_mask:0xf bank_mask:0xf
	v_fmac_f32_dpp v174, v94, v196 row_shl:14 row_mask:0xf bank_mask:0xf
	v_fmac_f32_dpp v175, v95, v197 row_shl:14 row_mask:0xf bank_mask:0xf
	v_fmac_f32_dpp v176, v72, v210 row_shl:14 row_mask:0xf bank_mask:0xf
	v_fmac_f32_dpp v177, v73, v211 row_shl:14 row_mask:0xf bank_mask:0xf
	v_fmac_f32_dpp v178, v74, v212 row_shl:14 row_mask:0xf bank_mask:0xf
	v_fmac_f32_dpp v179, v75, v213 row_shl:14 row_mask:0xf bank_mask:0xf
	v_pk_mul_f32 v[180:181], v[166:167], v[172:173]
	v_pk_mul_f32 v[182:183], v[166:167], v[174:175]
	v_pk_mul_f32 v[180:181], v[172:173], v[180:181]
	v_pk_mul_f32 v[182:183], v[174:175], v[182:183]
	v_pk_fma_f32 v[180:181], v[172:173], v[180:181], v[172:173]
	v_pk_fma_f32 v[182:183], v[174:175], v[182:183], v[174:175]
	v_pk_mul_f32 v[180:181], v[250:251], v[180:181]
	v_pk_mul_f32 v[182:183], v[250:251], v[182:183]
	v_exp_f32_e32 v180, v180
	v_exp_f32_e32 v181, v181
	v_exp_f32_e32 v182, v182
	v_exp_f32_e32 v183, v183
	v_pk_add_f32 v[180:181], v[180:181], 1.0 op_sel_hi:[1,0]
	v_pk_add_f32 v[182:183], v[182:183], 1.0 op_sel_hi:[1,0]
	v_rcp_f32_e32 v180, v180
	v_rcp_f32_e32 v181, v181
	v_rcp_f32_e32 v182, v182
	v_rcp_f32_e32 v183, v183
	v_pk_mul_f32 v[172:173], v[172:173], v[180:181]
	v_pk_mul_f32 v[174:175], v[174:175], v[182:183]
	v_pk_mul_f32 v[172:173], v[172:173], v[176:177]
	v_pk_mul_f32 v[174:175], v[174:175], v[178:179]
	v_cvt_pk_bf16_f32 v86, v172, v173
	v_cvt_pk_bf16_f32 v87, v174, v175
	v_add_u32_e32 v241, 0x42000, v235
	global_store_dwordx4 v241, v[84:87], s[56:57]
	v_pk_fma_f32 v[172:173], v[202:203], v[92:93], v[206:207]
	v_pk_fma_f32 v[174:175], v[204:205], v[94:95], v[208:209]
	v_pk_fma_f32 v[176:177], v[218:219], v[72:73], v[222:223]
	v_pk_fma_f32 v[178:179], v[220:221], v[74:75], v[224:225]
	v_fmac_f32_dpp v172, v92, v198 row_shr:1 row_mask:0xf bank_mask:0xf
	v_fmac_f32_dpp v173, v93, v199 row_shr:1 row_mask:0xf bank_mask:0xf
	v_fmac_f32_dpp v174, v94, v200 row_shr:1 row_mask:0xf bank_mask:0xf
	v_fmac_f32_dpp v175, v95, v201 row_shr:1 row_mask:0xf bank_mask:0xf
	v_fmac_f32_dpp v176, v72, v214 row_shr:1 row_mask:0xf bank_mask:0xf
	v_fmac_f32_dpp v177, v73, v215 row_shr:1 row_mask:0xf bank_mask:0xf
	v_fmac_f32_dpp v178, v74, v216 row_shr:1 row_mask:0xf bank_mask:0xf
	v_fmac_f32_dpp v179, v75, v217 row_shr:1 row_mask:0xf bank_mask:0xf
	v_fmac_f32_dpp v172, v92, v194 row_shr:2 row_mask:0xf bank_mask:0xf
	v_fmac_f32_dpp v173, v93, v195 row_shr:2 row_mask:0xf bank_mask:0xf
	v_fmac_f32_dpp v174, v94, v196 row_shr:2 row_mask:0xf bank_mask:0xf
	v_fmac_f32_dpp v175, v95, v197 row_shr:2 row_mask:0xf bank_mask:0xf
	v_fmac_f32_dpp v176, v72, v210 row_shr:2 row_mask:0xf bank_mask:0xf
	v_fmac_f32_dpp v177, v73, v211 row_shr:2 row_mask:0xf bank_mask:0xf
	v_fmac_f32_dpp v178, v74, v212 row_shr:2 row_mask:0xf bank_mask:0xf
	v_fmac_f32_dpp v179, v75, v213 row_shr:2 row_mask:0xf bank_mask:0xf
	v_fmac_f32_dpp v172, v108, v198 row_shl:15 row_mask:0xf bank_mask:0xf
	v_fmac_f32_dpp v173, v109, v199 row_shl:15 row_mask:0xf bank_mask:0xf
	v_fmac_f32_dpp v174, v110, v200 row_shl:15 row_mask:0xf bank_mask:0xf
	v_fmac_f32_dpp v175, v111, v201 row_shl:15 row_mask:0xf bank_mask:0xf
	v_fmac_f32_dpp v176, v88, v214 row_shl:15 row_mask:0xf bank_mask:0xf
	v_fmac_f32_dpp v177, v89, v215 row_shl:15 row_mask:0xf bank_mask:0xf
	v_fmac_f32_dpp v178, v90, v216 row_shl:15 row_mask:0xf bank_mask:0xf
	v_fmac_f32_dpp v179, v91, v217 row_shl:15 row_mask:0xf bank_mask:0xf
	v_fmac_f32_dpp v172, v108, v194 row_shl:14 row_mask:0xf bank_mask:0xf
	v_fmac_f32_dpp v173, v109, v195 row_shl:14 row_mask:0xf bank_mask:0xf
	v_fmac_f32_dpp v174, v110, v196 row_shl:14 row_mask:0xf bank_mask:0xf
	v_fmac_f32_dpp v175, v111, v197 row_shl:14 row_mask:0xf bank_mask:0xf
	v_fmac_f32_dpp v176, v88, v210 row_shl:14 row_mask:0xf bank_mask:0xf
	v_fmac_f32_dpp v177, v89, v211 row_shl:14 row_mask:0xf bank_mask:0xf
	v_fmac_f32_dpp v178, v90, v212 row_shl:14 row_mask:0xf bank_mask:0xf
	v_fmac_f32_dpp v179, v91, v213 row_shl:14 row_mask:0xf bank_mask:0xf
	v_pk_mul_f32 v[180:181], v[166:167], v[172:173]
	v_pk_mul_f32 v[182:183], v[166:167], v[174:175]
	v_pk_mul_f32 v[180:181], v[172:173], v[180:181]
	v_pk_mul_f32 v[182:183], v[174:175], v[182:183]
	v_pk_fma_f32 v[180:181], v[172:173], v[180:181], v[172:173]
	v_pk_fma_f32 v[182:183], v[174:175], v[182:183], v[174:175]
	v_pk_mul_f32 v[180:181], v[250:251], v[180:181]
	v_pk_mul_f32 v[182:183], v[250:251], v[182:183]
	v_exp_f32_e32 v180, v180
	v_exp_f32_e32 v181, v181
	v_exp_f32_e32 v182, v182
	v_exp_f32_e32 v183, v183
	v_pk_add_f32 v[180:181], v[180:181], 1.0 op_sel_hi:[1,0]
	v_pk_add_f32 v[182:183], v[182:183], 1.0 op_sel_hi:[1,0]
	v_rcp_f32_e32 v180, v180
	v_rcp_f32_e32 v181, v181
	v_rcp_f32_e32 v182, v182
	v_rcp_f32_e32 v183, v183
	v_pk_mul_f32 v[172:173], v[172:173], v[180:181]
	v_pk_mul_f32 v[174:175], v[174:175], v[182:183]
	v_pk_mul_f32 v[172:173], v[172:173], v[176:177]
	v_pk_mul_f32 v[174:175], v[174:175], v[178:179]
	v_cvt_pk_bf16_f32 v102, v172, v173
	v_cvt_pk_bf16_f32 v103, v174, v175
	v_add_u32_e32 v241, 0x2c000, v235
	global_store_dwordx4 v241, v[100:103], s[56:57]
	v_pk_fma_f32 v[172:173], v[202:203], v[108:109], v[206:207]
	v_pk_fma_f32 v[174:175], v[204:205], v[110:111], v[208:209]
	v_pk_fma_f32 v[176:177], v[218:219], v[88:89], v[222:223]
	v_pk_fma_f32 v[178:179], v[220:221], v[90:91], v[224:225]
	v_fmac_f32_dpp v172, v108, v198 row_shr:1 row_mask:0xf bank_mask:0xf
	v_fmac_f32_dpp v173, v109, v199 row_shr:1 row_mask:0xf bank_mask:0xf
	v_fmac_f32_dpp v174, v110, v200 row_shr:1 row_mask:0xf bank_mask:0xf
	v_fmac_f32_dpp v175, v111, v201 row_shr:1 row_mask:0xf bank_mask:0xf
	v_fmac_f32_dpp v176, v88, v214 row_shr:1 row_mask:0xf bank_mask:0xf
	v_fmac_f32_dpp v177, v89, v215 row_shr:1 row_mask:0xf bank_mask:0xf
	v_fmac_f32_dpp v178, v90, v216 row_shr:1 row_mask:0xf bank_mask:0xf
	v_fmac_f32_dpp v179, v91, v217 row_shr:1 row_mask:0xf bank_mask:0xf
	v_fmac_f32_dpp v172, v108, v194 row_shr:2 row_mask:0xf bank_mask:0xf
	v_fmac_f32_dpp v173, v109, v195 row_shr:2 row_mask:0xf bank_mask:0xf
	v_fmac_f32_dpp v174, v110, v196 row_shr:2 row_mask:0xf bank_mask:0xf
	v_fmac_f32_dpp v175, v111, v197 row_shr:2 row_mask:0xf bank_mask:0xf
	v_fmac_f32_dpp v176, v88, v210 row_shr:2 row_mask:0xf bank_mask:0xf
	v_fmac_f32_dpp v177, v89, v211 row_shr:2 row_mask:0xf bank_mask:0xf
	v_fmac_f32_dpp v178, v90, v212 row_shr:2 row_mask:0xf bank_mask:0xf
	v_fmac_f32_dpp v179, v91, v213 row_shr:2 row_mask:0xf bank_mask:0xf
	v_fmac_f32_dpp v172, v120, v198 row_shl:15 row_mask:0xf bank_mask:0xf
	v_fmac_f32_dpp v173, v121, v199 row_shl:15 row_mask:0xf bank_mask:0xf
	v_fmac_f32_dpp v174, v122, v200 row_shl:15 row_mask:0xf bank_mask:0xf
	v_fmac_f32_dpp v175, v123, v201 row_shl:15 row_mask:0xf bank_mask:0xf
	v_fmac_f32_dpp v176, v104, v214 row_shl:15 row_mask:0xf bank_mask:0xf
	v_fmac_f32_dpp v177, v105, v215 row_shl:15 row_mask:0xf bank_mask:0xf
	v_fmac_f32_dpp v178, v106, v216 row_shl:15 row_mask:0xf bank_mask:0xf
	v_fmac_f32_dpp v179, v107, v217 row_shl:15 row_mask:0xf bank_mask:0xf
	v_fmac_f32_dpp v172, v120, v194 row_shl:14 row_mask:0xf bank_mask:0xf
	v_fmac_f32_dpp v173, v121, v195 row_shl:14 row_mask:0xf bank_mask:0xf
	v_fmac_f32_dpp v174, v122, v196 row_shl:14 row_mask:0xf bank_mask:0xf
	v_fmac_f32_dpp v175, v123, v197 row_shl:14 row_mask:0xf bank_mask:0xf
	v_fmac_f32_dpp v176, v104, v210 row_shl:14 row_mask:0xf bank_mask:0xf
	v_fmac_f32_dpp v177, v105, v211 row_shl:14 row_mask:0xf bank_mask:0xf
	v_fmac_f32_dpp v178, v106, v212 row_shl:14 row_mask:0xf bank_mask:0xf
	v_fmac_f32_dpp v179, v107, v213 row_shl:14 row_mask:0xf bank_mask:0xf
	v_pk_mul_f32 v[180:181], v[166:167], v[172:173]
	v_pk_mul_f32 v[182:183], v[166:167], v[174:175]
	v_pk_mul_f32 v[180:181], v[172:173], v[180:181]
	v_pk_mul_f32 v[182:183], v[174:175], v[182:183]
	v_pk_fma_f32 v[180:181], v[172:173], v[180:181], v[172:173]
	v_pk_fma_f32 v[182:183], v[174:175], v[182:183], v[174:175]
	v_pk_mul_f32 v[180:181], v[250:251], v[180:181]
	v_pk_mul_f32 v[182:183], v[250:251], v[182:183]
	v_exp_f32_e32 v180, v180
	v_exp_f32_e32 v181, v181
	v_exp_f32_e32 v182, v182
	v_exp_f32_e32 v183, v183
	v_pk_add_f32 v[180:181], v[180:181], 1.0 op_sel_hi:[1,0]
	v_pk_add_f32 v[182:183], v[182:183], 1.0 op_sel_hi:[1,0]
	v_rcp_f32_e32 v180, v180
	v_rcp_f32_e32 v181, v181
	v_rcp_f32_e32 v182, v182
	v_rcp_f32_e32 v183, v183
	v_pk_mul_f32 v[172:173], v[172:173], v[180:181]
	v_pk_mul_f32 v[174:175], v[174:175], v[182:183]
	v_pk_mul_f32 v[172:173], v[172:173], v[176:177]
	v_pk_mul_f32 v[174:175], v[174:175], v[178:179]
	v_cvt_pk_bf16_f32 v114, v172, v173
	v_cvt_pk_bf16_f32 v115, v174, v175
	v_add_u32_e32 v241, 0x16000, v235
	global_store_dwordx4 v241, v[112:115], s[56:57]
	v_pk_fma_f32 v[172:173], v[202:203], v[120:121], v[206:207]
	v_pk_fma_f32 v[174:175], v[204:205], v[122:123], v[208:209]
	v_pk_fma_f32 v[176:177], v[218:219], v[104:105], v[222:223]
	v_pk_fma_f32 v[178:179], v[220:221], v[106:107], v[224:225]
	v_fmac_f32_dpp v172, v120, v198 row_shr:1 row_mask:0xf bank_mask:0xf
	v_fmac_f32_dpp v173, v121, v199 row_shr:1 row_mask:0xf bank_mask:0xf
	v_fmac_f32_dpp v174, v122, v200 row_shr:1 row_mask:0xf bank_mask:0xf
	v_fmac_f32_dpp v175, v123, v201 row_shr:1 row_mask:0xf bank_mask:0xf
	v_fmac_f32_dpp v176, v104, v214 row_shr:1 row_mask:0xf bank_mask:0xf
	v_fmac_f32_dpp v177, v105, v215 row_shr:1 row_mask:0xf bank_mask:0xf
	v_fmac_f32_dpp v178, v106, v216 row_shr:1 row_mask:0xf bank_mask:0xf
	v_fmac_f32_dpp v179, v107, v217 row_shr:1 row_mask:0xf bank_mask:0xf
	v_fmac_f32_dpp v172, v120, v194 row_shr:2 row_mask:0xf bank_mask:0xf
	v_fmac_f32_dpp v173, v121, v195 row_shr:2 row_mask:0xf bank_mask:0xf
	v_fmac_f32_dpp v174, v122, v196 row_shr:2 row_mask:0xf bank_mask:0xf
	v_fmac_f32_dpp v175, v123, v197 row_shr:2 row_mask:0xf bank_mask:0xf
	v_fmac_f32_dpp v176, v104, v210 row_shr:2 row_mask:0xf bank_mask:0xf
	v_fmac_f32_dpp v177, v105, v211 row_shr:2 row_mask:0xf bank_mask:0xf
	v_fmac_f32_dpp v178, v106, v212 row_shr:2 row_mask:0xf bank_mask:0xf
	v_fmac_f32_dpp v179, v107, v213 row_shr:2 row_mask:0xf bank_mask:0xf
	v_fmac_f32_dpp v172, v128, v198 row_shl:15 row_mask:0xf bank_mask:0xf
	v_fmac_f32_dpp v173, v129, v199 row_shl:15 row_mask:0xf bank_mask:0xf
	v_fmac_f32_dpp v174, v130, v200 row_shl:15 row_mask:0xf bank_mask:0xf
	v_fmac_f32_dpp v175, v131, v201 row_shl:15 row_mask:0xf bank_mask:0xf
	v_fmac_f32_dpp v176, v132, v214 row_shl:15 row_mask:0xf bank_mask:0xf
	v_fmac_f32_dpp v177, v133, v215 row_shl:15 row_mask:0xf bank_mask:0xf
	v_fmac_f32_dpp v178, v134, v216 row_shl:15 row_mask:0xf bank_mask:0xf
	v_fmac_f32_dpp v179, v135, v217 row_shl:15 row_mask:0xf bank_mask:0xf
	v_fmac_f32_dpp v172, v128, v194 row_shl:14 row_mask:0xf bank_mask:0xf
	v_fmac_f32_dpp v173, v129, v195 row_shl:14 row_mask:0xf bank_mask:0xf
	v_fmac_f32_dpp v174, v130, v196 row_shl:14 row_mask:0xf bank_mask:0xf
	v_fmac_f32_dpp v175, v131, v197 row_shl:14 row_mask:0xf bank_mask:0xf
	v_fmac_f32_dpp v176, v132, v210 row_shl:14 row_mask:0xf bank_mask:0xf
	v_fmac_f32_dpp v177, v133, v211 row_shl:14 row_mask:0xf bank_mask:0xf
	v_fmac_f32_dpp v178, v134, v212 row_shl:14 row_mask:0xf bank_mask:0xf
	v_fmac_f32_dpp v179, v135, v213 row_shl:14 row_mask:0xf bank_mask:0xf
	v_pk_mul_f32 v[180:181], v[166:167], v[172:173]
	v_pk_mul_f32 v[182:183], v[166:167], v[174:175]
	v_pk_mul_f32 v[180:181], v[172:173], v[180:181]
	v_pk_mul_f32 v[182:183], v[174:175], v[182:183]
	v_pk_fma_f32 v[180:181], v[172:173], v[180:181], v[172:173]
	v_pk_fma_f32 v[182:183], v[174:175], v[182:183], v[174:175]
	v_pk_mul_f32 v[180:181], v[250:251], v[180:181]
	v_pk_mul_f32 v[182:183], v[250:251], v[182:183]
	v_exp_f32_e32 v180, v180
	v_exp_f32_e32 v181, v181
	v_exp_f32_e32 v182, v182
	v_exp_f32_e32 v183, v183
	v_pk_add_f32 v[180:181], v[180:181], 1.0 op_sel_hi:[1,0]
	v_pk_add_f32 v[182:183], v[182:183], 1.0 op_sel_hi:[1,0]
	v_rcp_f32_e32 v180, v180
	v_rcp_f32_e32 v181, v181
	v_rcp_f32_e32 v182, v182
	v_rcp_f32_e32 v183, v183
	v_pk_mul_f32 v[172:173], v[172:173], v[180:181]
	v_pk_mul_f32 v[174:175], v[174:175], v[182:183]
	v_pk_mul_f32 v[172:173], v[172:173], v[176:177]
	v_pk_mul_f32 v[174:175], v[174:175], v[178:179]
	v_cvt_pk_bf16_f32 v126, v172, v173
	v_cvt_pk_bf16_f32 v127, v174, v175
	v_add_u32_e32 v241, 0x0, v235
	s_cmp_lg_u32 s33, 0
	s_cbranch_scc1 .Lepi9_wr1_3
	s_andn2_b64 exec, exec, s[52:53]
	global_store_dwordx4 v241, v[124:127], s[56:57]
	s_mov_b64 exec, -1
	s_branch .Lepi9_wrend_3

.Lepi9_wrend_3:
	v_pk_fma_f32 v[172:173], v[202:203], v[12:13], v[206:207]
	v_pk_fma_f32 v[174:175], v[204:205], v[14:15], v[208:209]
	v_pk_fma_f32 v[176:177], v[218:219], v[0:1], v[222:223]
	v_pk_fma_f32 v[178:179], v[220:221], v[2:3], v[224:225]
	v_fmac_f32_dpp v172, v12, v198 row_shr:1 row_mask:0xf bank_mask:0xf
	v_fmac_f32_dpp v173, v13, v199 row_shr:1 row_mask:0xf bank_mask:0xf
	v_fmac_f32_dpp v174, v14, v200 row_shr:1 row_mask:0xf bank_mask:0xf
	v_fmac_f32_dpp v175, v15, v201 row_shr:1 row_mask:0xf bank_mask:0xf
	v_fmac_f32_dpp v176, v0, v214 row_shr:1 row_mask:0xf bank_mask:0xf
	v_fmac_f32_dpp v177, v1, v215 row_shr:1 row_mask:0xf bank_mask:0xf
	v_fmac_f32_dpp v178, v2, v216 row_shr:1 row_mask:0xf bank_mask:0xf
	v_fmac_f32_dpp v179, v3, v217 row_shr:1 row_mask:0xf bank_mask:0xf
	v_fmac_f32_dpp v172, v12, v194 row_shr:2 row_mask:0xf bank_mask:0xf
	v_fmac_f32_dpp v173, v13, v195 row_shr:2 row_mask:0xf bank_mask:0xf
	v_fmac_f32_dpp v174, v14, v196 row_shr:2 row_mask:0xf bank_mask:0xf
	v_fmac_f32_dpp v175, v15, v197 row_shr:2 row_mask:0xf bank_mask:0xf
	v_fmac_f32_dpp v176, v0, v210 row_shr:2 row_mask:0xf bank_mask:0xf
	v_fmac_f32_dpp v177, v1, v211 row_shr:2 row_mask:0xf bank_mask:0xf
	v_fmac_f32_dpp v178, v2, v212 row_shr:2 row_mask:0xf bank_mask:0xf
	v_fmac_f32_dpp v179, v3, v213 row_shr:2 row_mask:0xf bank_mask:0xf
	v_fmac_f32_dpp v172, v28, v198 row_shl:15 row_mask:0xf bank_mask:0xf
	v_fmac_f32_dpp v173, v29, v199 row_shl:15 row_mask:0xf bank_mask:0xf
	v_fmac_f32_dpp v174, v30, v200 row_shl:15 row_mask:0xf bank_mask:0xf
	v_fmac_f32_dpp v175, v31, v201 row_shl:15 row_mask:0xf bank_mask:0xf
	v_fmac_f32_dpp v176, v8, v214 row_shl:15 row_mask:0xf bank_mask:0xf
	v_fmac_f32_dpp v177, v9, v215 row_shl:15 row_mask:0xf bank_mask:0xf
	v_fmac_f32_dpp v178, v10, v216 row_shl:15 row_mask:0xf bank_mask:0xf
	v_fmac_f32_dpp v179, v11, v217 row_shl:15 row_mask:0xf bank_mask:0xf
	v_fmac_f32_dpp v172, v28, v194 row_shl:14 row_mask:0xf bank_mask:0xf
	v_fmac_f32_dpp v173, v29, v195 row_shl:14 row_mask:0xf bank_mask:0xf
	v_fmac_f32_dpp v174, v30, v196 row_shl:14 row_mask:0xf bank_mask:0xf
	v_fmac_f32_dpp v175, v31, v197 row_shl:14 row_mask:0xf bank_mask:0xf
	v_fmac_f32_dpp v176, v8, v210 row_shl:14 row_mask:0xf bank_mask:0xf
	v_fmac_f32_dpp v177, v9, v211 row_shl:14 row_mask:0xf bank_mask:0xf
	v_fmac_f32_dpp v178, v10, v212 row_shl:14 row_mask:0xf bank_mask:0xf
	v_fmac_f32_dpp v179, v11, v213 row_shl:14 row_mask:0xf bank_mask:0xf
	v_pk_mul_f32 v[180:181], v[166:167], v[172:173]
	v_pk_mul_f32 v[182:183], v[166:167], v[174:175]
	v_pk_mul_f32 v[180:181], v[172:173], v[180:181]
	v_pk_mul_f32 v[182:183], v[174:175], v[182:183]
	v_pk_fma_f32 v[180:181], v[172:173], v[180:181], v[172:173]
	v_pk_fma_f32 v[182:183], v[174:175], v[182:183], v[174:175]
	v_pk_mul_f32 v[180:181], v[250:251], v[180:181]
	v_pk_mul_f32 v[182:183], v[250:251], v[182:183]
	v_exp_f32_e32 v180, v180
	v_exp_f32_e32 v181, v181
	v_exp_f32_e32 v182, v182
	v_exp_f32_e32 v183, v183
	v_pk_add_f32 v[180:181], v[180:181], 1.0 op_sel_hi:[1,0]
	v_pk_add_f32 v[182:183], v[182:183], 1.0 op_sel_hi:[1,0]
	v_rcp_f32_e32 v180, v180
	v_rcp_f32_e32 v181, v181
	v_rcp_f32_e32 v182, v182
	v_rcp_f32_e32 v183, v183
	v_pk_mul_f32 v[172:173], v[172:173], v[180:181]
	v_pk_mul_f32 v[174:175], v[174:175], v[182:183]
	v_pk_mul_f32 v[172:173], v[172:173], v[176:177]
	v_pk_mul_f32 v[174:175], v[174:175], v[178:179]
	v_cvt_pk_bf16_f32 v22, v172, v173
	v_cvt_pk_bf16_f32 v23, v174, v175
	v_add_u32_e32 v241, 0xf2000, v235
	global_store_dwordx4 v241, v[20:23], s[56:57]
	v_pk_fma_f32 v[172:173], v[202:203], v[28:29], v[206:207]
	v_pk_fma_f32 v[174:175], v[204:205], v[30:31], v[208:209]
	v_pk_fma_f32 v[176:177], v[218:219], v[8:9], v[222:223]
	v_pk_fma_f32 v[178:179], v[220:221], v[10:11], v[224:225]
	v_fmac_f32_dpp v172, v28, v198 row_shr:1 row_mask:0xf bank_mask:0xf
	v_fmac_f32_dpp v173, v29, v199 row_shr:1 row_mask:0xf bank_mask:0xf
	v_fmac_f32_dpp v174, v30, v200 row_shr:1 row_mask:0xf bank_mask:0xf
	v_fmac_f32_dpp v175, v31, v201 row_shr:1 row_mask:0xf bank_mask:0xf
	v_fmac_f32_dpp v176, v8, v214 row_shr:1 row_mask:0xf bank_mask:0xf
	v_fmac_f32_dpp v177, v9, v215 row_shr:1 row_mask:0xf bank_mask:0xf
	v_fmac_f32_dpp v178, v10, v216 row_shr:1 row_mask:0xf bank_mask:0xf
	v_fmac_f32_dpp v179, v11, v217 row_shr:1 row_mask:0xf bank_mask:0xf
	v_fmac_f32_dpp v172, v28, v194 row_shr:2 row_mask:0xf bank_mask:0xf
	v_fmac_f32_dpp v173, v29, v195 row_shr:2 row_mask:0xf bank_mask:0xf
	v_fmac_f32_dpp v174, v30, v196 row_shr:2 row_mask:0xf bank_mask:0xf
	v_fmac_f32_dpp v175, v31, v197 row_shr:2 row_mask:0xf bank_mask:0xf
	v_fmac_f32_dpp v176, v8, v210 row_shr:2 row_mask:0xf bank_mask:0xf
	v_fmac_f32_dpp v177, v9, v211 row_shr:2 row_mask:0xf bank_mask:0xf
	v_fmac_f32_dpp v178, v10, v212 row_shr:2 row_mask:0xf bank_mask:0xf
	v_fmac_f32_dpp v179, v11, v213 row_shr:2 row_mask:0xf bank_mask:0xf
	v_fmac_f32_dpp v172, v44, v198 row_shl:15 row_mask:0xf bank_mask:0xf
	v_fmac_f32_dpp v173, v45, v199 row_shl:15 row_mask:0xf bank_mask:0xf
	v_fmac_f32_dpp v174, v46, v200 row_shl:15 row_mask:0xf bank_mask:0xf
	v_fmac_f32_dpp v175, v47, v201 row_shl:15 row_mask:0xf bank_mask:0xf
	v_fmac_f32_dpp v176, v24, v214 row_shl:15 row_mask:0xf bank_mask:0xf
	v_fmac_f32_dpp v177, v25, v215 row_shl:15 row_mask:0xf bank_mask:0xf
	v_fmac_f32_dpp v178, v26, v216 row_shl:15 row_mask:0xf bank_mask:0xf
	v_fmac_f32_dpp v179, v27, v217 row_shl:15 row_mask:0xf bank_mask:0xf
	v_fmac_f32_dpp v172, v44, v194 row_shl:14 row_mask:0xf bank_mask:0xf
	v_fmac_f32_dpp v173, v45, v195 row_shl:14 row_mask:0xf bank_mask:0xf
	v_fmac_f32_dpp v174, v46, v196 row_shl:14 row_mask:0xf bank_mask:0xf
	v_fmac_f32_dpp v175, v47, v197 row_shl:14 row_mask:0xf bank_mask:0xf
	v_fmac_f32_dpp v176, v24, v210 row_shl:14 row_mask:0xf bank_mask:0xf
	v_fmac_f32_dpp v177, v25, v211 row_shl:14 row_mask:0xf bank_mask:0xf
	v_fmac_f32_dpp v178, v26, v212 row_shl:14 row_mask:0xf bank_mask:0xf
	v_fmac_f32_dpp v179, v27, v213 row_shl:14 row_mask:0xf bank_mask:0xf
	v_pk_mul_f32 v[180:181], v[166:167], v[172:173]
	v_pk_mul_f32 v[182:183], v[166:167], v[174:175]
	v_pk_mul_f32 v[180:181], v[172:173], v[180:181]
	v_pk_mul_f32 v[182:183], v[174:175], v[182:183]
	v_pk_fma_f32 v[180:181], v[172:173], v[180:181], v[172:173]
	v_pk_fma_f32 v[182:183], v[174:175], v[182:183], v[174:175]
	v_pk_mul_f32 v[180:181], v[250:251], v[180:181]
	v_pk_mul_f32 v[182:183], v[250:251], v[182:183]
	v_exp_f32_e32 v180, v180
	v_exp_f32_e32 v181, v181
	v_exp_f32_e32 v182, v182
	v_exp_f32_e32 v183, v183
	v_pk_add_f32 v[180:181], v[180:181], 1.0 op_sel_hi:[1,0]
	v_pk_add_f32 v[182:183], v[182:183], 1.0 op_sel_hi:[1,0]
	v_rcp_f32_e32 v180, v180
	v_rcp_f32_e32 v181, v181
	v_rcp_f32_e32 v182, v182
	v_rcp_f32_e32 v183, v183
	v_pk_mul_f32 v[172:173], v[172:173], v[180:181]
	v_pk_mul_f32 v[174:175], v[174:175], v[182:183]
	v_pk_mul_f32 v[172:173], v[172:173], v[176:177]
	v_pk_mul_f32 v[174:175], v[174:175], v[178:179]
	v_cvt_pk_bf16_f32 v38, v172, v173
	v_cvt_pk_bf16_f32 v39, v174, v175
	v_add_u32_e32 v241, 0xdc000, v235
	global_store_dwordx4 v241, v[36:39], s[56:57]
	v_pk_fma_f32 v[172:173], v[202:203], v[44:45], v[206:207]
	v_pk_fma_f32 v[174:175], v[204:205], v[46:47], v[208:209]
	v_pk_fma_f32 v[176:177], v[218:219], v[24:25], v[222:223]
	v_pk_fma_f32 v[178:179], v[220:221], v[26:27], v[224:225]
	v_fmac_f32_dpp v172, v44, v198 row_shr:1 row_mask:0xf bank_mask:0xf
	v_fmac_f32_dpp v173, v45, v199 row_shr:1 row_mask:0xf bank_mask:0xf
	v_fmac_f32_dpp v174, v46, v200 row_shr:1 row_mask:0xf bank_mask:0xf
	v_fmac_f32_dpp v175, v47, v201 row_shr:1 row_mask:0xf bank_mask:0xf
	v_fmac_f32_dpp v176, v24, v214 row_shr:1 row_mask:0xf bank_mask:0xf
	v_fmac_f32_dpp v177, v25, v215 row_shr:1 row_mask:0xf bank_mask:0xf
	v_fmac_f32_dpp v178, v26, v216 row_shr:1 row_mask:0xf bank_mask:0xf
	v_fmac_f32_dpp v179, v27, v217 row_shr:1 row_mask:0xf bank_mask:0xf
	v_fmac_f32_dpp v172, v44, v194 row_shr:2 row_mask:0xf bank_mask:0xf
	v_fmac_f32_dpp v173, v45, v195 row_shr:2 row_mask:0xf bank_mask:0xf
	v_fmac_f32_dpp v174, v46, v196 row_shr:2 row_mask:0xf bank_mask:0xf
	v_fmac_f32_dpp v175, v47, v197 row_shr:2 row_mask:0xf bank_mask:0xf
	v_fmac_f32_dpp v176, v24, v210 row_shr:2 row_mask:0xf bank_mask:0xf
	v_fmac_f32_dpp v177, v25, v211 row_shr:2 row_mask:0xf bank_mask:0xf
	v_fmac_f32_dpp v178, v26, v212 row_shr:2 row_mask:0xf bank_mask:0xf
	v_fmac_f32_dpp v179, v27, v213 row_shr:2 row_mask:0xf bank_mask:0xf
	v_fmac_f32_dpp v172, v56, v198 row_shl:15 row_mask:0xf bank_mask:0xf
	v_fmac_f32_dpp v173, v57, v199 row_shl:15 row_mask:0xf bank_mask:0xf
	v_fmac_f32_dpp v174, v58, v200 row_shl:15 row_mask:0xf bank_mask:0xf
	v_fmac_f32_dpp v175, v59, v201 row_shl:15 row_mask:0xf bank_mask:0xf
	v_fmac_f32_dpp v176, v40, v214 row_shl:15 row_mask:0xf bank_mask:0xf
	v_fmac_f32_dpp v177, v41, v215 row_shl:15 row_mask:0xf bank_mask:0xf
	v_fmac_f32_dpp v178, v42, v216 row_shl:15 row_mask:0xf bank_mask:0xf
	v_fmac_f32_dpp v179, v43, v217 row_shl:15 row_mask:0xf bank_mask:0xf
	v_fmac_f32_dpp v172, v56, v194 row_shl:14 row_mask:0xf bank_mask:0xf
	v_fmac_f32_dpp v173, v57, v195 row_shl:14 row_mask:0xf bank_mask:0xf
	v_fmac_f32_dpp v174, v58, v196 row_shl:14 row_mask:0xf bank_mask:0xf
	v_fmac_f32_dpp v175, v59, v197 row_shl:14 row_mask:0xf bank_mask:0xf
	v_fmac_f32_dpp v176, v40, v210 row_shl:14 row_mask:0xf bank_mask:0xf
	v_fmac_f32_dpp v177, v41, v211 row_shl:14 row_mask:0xf bank_mask:0xf
	v_fmac_f32_dpp v178, v42, v212 row_shl:14 row_mask:0xf bank_mask:0xf
	v_fmac_f32_dpp v179, v43, v213 row_shl:14 row_mask:0xf bank_mask:0xf
	v_pk_mul_f32 v[180:181], v[166:167], v[172:173]
	v_pk_mul_f32 v[182:183], v[166:167], v[174:175]
	v_pk_mul_f32 v[180:181], v[172:173], v[180:181]
	v_pk_mul_f32 v[182:183], v[174:175], v[182:183]
	v_pk_fma_f32 v[180:181], v[172:173], v[180:181], v[172:173]
	v_pk_fma_f32 v[182:183], v[174:175], v[182:183], v[174:175]
	v_pk_mul_f32 v[180:181], v[250:251], v[180:181]
	v_pk_mul_f32 v[182:183], v[250:251], v[182:183]
	v_exp_f32_e32 v180, v180
	v_exp_f32_e32 v181, v181
	v_exp_f32_e32 v182, v182
	v_exp_f32_e32 v183, v183
	v_pk_add_f32 v[180:181], v[180:181], 1.0 op_sel_hi:[1,0]
	v_pk_add_f32 v[182:183], v[182:183], 1.0 op_sel_hi:[1,0]
	v_rcp_f32_e32 v180, v180
	v_rcp_f32_e32 v181, v181
	v_rcp_f32_e32 v182, v182
	v_rcp_f32_e32 v183, v183
	v_pk_mul_f32 v[172:173], v[172:173], v[180:181]
	v_pk_mul_f32 v[174:175], v[174:175], v[182:183]
	v_pk_mul_f32 v[172:173], v[172:173], v[176:177]
	v_pk_mul_f32 v[174:175], v[174:175], v[178:179]
	v_cvt_pk_bf16_f32 v54, v172, v173
	v_cvt_pk_bf16_f32 v55, v174, v175
	v_add_u32_e32 v241, 0xc6000, v235
	global_store_dwordx4 v241, v[52:55], s[56:57]
	v_pk_fma_f32 v[172:173], v[202:203], v[56:57], v[206:207]
	v_pk_fma_f32 v[174:175], v[204:205], v[58:59], v[208:209]
	v_pk_fma_f32 v[176:177], v[218:219], v[40:41], v[222:223]
	v_pk_fma_f32 v[178:179], v[220:221], v[42:43], v[224:225]
	v_fmac_f32_dpp v172, v56, v198 row_shr:1 row_mask:0xf bank_mask:0xf
	v_fmac_f32_dpp v173, v57, v199 row_shr:1 row_mask:0xf bank_mask:0xf
	v_fmac_f32_dpp v174, v58, v200 row_shr:1 row_mask:0xf bank_mask:0xf
	v_fmac_f32_dpp v175, v59, v201 row_shr:1 row_mask:0xf bank_mask:0xf
	v_fmac_f32_dpp v176, v40, v214 row_shr:1 row_mask:0xf bank_mask:0xf
	v_fmac_f32_dpp v177, v41, v215 row_shr:1 row_mask:0xf bank_mask:0xf
	v_fmac_f32_dpp v178, v42, v216 row_shr:1 row_mask:0xf bank_mask:0xf
	v_fmac_f32_dpp v179, v43, v217 row_shr:1 row_mask:0xf bank_mask:0xf
	v_fmac_f32_dpp v172, v56, v194 row_shr:2 row_mask:0xf bank_mask:0xf
	v_fmac_f32_dpp v173, v57, v195 row_shr:2 row_mask:0xf bank_mask:0xf
	v_fmac_f32_dpp v174, v58, v196 row_shr:2 row_mask:0xf bank_mask:0xf
	v_fmac_f32_dpp v175, v59, v197 row_shr:2 row_mask:0xf bank_mask:0xf
	v_fmac_f32_dpp v176, v40, v210 row_shr:2 row_mask:0xf bank_mask:0xf
	v_fmac_f32_dpp v177, v41, v211 row_shr:2 row_mask:0xf bank_mask:0xf
	v_fmac_f32_dpp v178, v42, v212 row_shr:2 row_mask:0xf bank_mask:0xf
	v_fmac_f32_dpp v179, v43, v213 row_shr:2 row_mask:0xf bank_mask:0xf
	v_fmac_f32_dpp v172, v136, v198 row_shl:15 row_mask:0xf bank_mask:0xf
	v_fmac_f32_dpp v173, v137, v199 row_shl:15 row_mask:0xf bank_mask:0xf
	v_fmac_f32_dpp v174, v138, v200 row_shl:15 row_mask:0xf bank_mask:0xf
	v_fmac_f32_dpp v175, v139, v201 row_shl:15 row_mask:0xf bank_mask:0xf
	v_fmac_f32_dpp v176, v140, v214 row_shl:15 row_mask:0xf bank_mask:0xf
	v_fmac_f32_dpp v177, v141, v215 row_shl:15 row_mask:0xf bank_mask:0xf
	v_fmac_f32_dpp v178, v142, v216 row_shl:15 row_mask:0xf bank_mask:0xf
	v_fmac_f32_dpp v179, v143, v217 row_shl:15 row_mask:0xf bank_mask:0xf
	v_fmac_f32_dpp v172, v136, v194 row_shl:14 row_mask:0xf bank_mask:0xf
	v_fmac_f32_dpp v173, v137, v195 row_shl:14 row_mask:0xf bank_mask:0xf
	v_fmac_f32_dpp v174, v138, v196 row_shl:14 row_mask:0xf bank_mask:0xf
	v_fmac_f32_dpp v175, v139, v197 row_shl:14 row_mask:0xf bank_mask:0xf
	v_fmac_f32_dpp v176, v140, v210 row_shl:14 row_mask:0xf bank_mask:0xf
	v_fmac_f32_dpp v177, v141, v211 row_shl:14 row_mask:0xf bank_mask:0xf
	v_fmac_f32_dpp v178, v142, v212 row_shl:14 row_mask:0xf bank_mask:0xf
	v_fmac_f32_dpp v179, v143, v213 row_shl:14 row_mask:0xf bank_mask:0xf
	v_pk_mul_f32 v[180:181], v[166:167], v[172:173]
	v_pk_mul_f32 v[182:183], v[166:167], v[174:175]
	v_pk_mul_f32 v[180:181], v[172:173], v[180:181]
	v_pk_mul_f32 v[182:183], v[174:175], v[182:183]
	v_pk_fma_f32 v[180:181], v[172:173], v[180:181], v[172:173]
	v_pk_fma_f32 v[182:183], v[174:175], v[182:183], v[174:175]
	v_pk_mul_f32 v[180:181], v[250:251], v[180:181]
	v_pk_mul_f32 v[182:183], v[250:251], v[182:183]
	v_exp_f32_e32 v180, v180
	v_exp_f32_e32 v181, v181
	v_exp_f32_e32 v182, v182
	v_exp_f32_e32 v183, v183
	v_pk_add_f32 v[180:181], v[180:181], 1.0 op_sel_hi:[1,0]
	v_pk_add_f32 v[182:183], v[182:183], 1.0 op_sel_hi:[1,0]
	v_rcp_f32_e32 v180, v180
	v_rcp_f32_e32 v181, v181
	v_rcp_f32_e32 v182, v182
	v_rcp_f32_e32 v183, v183
	v_pk_mul_f32 v[172:173], v[172:173], v[180:181]
	v_pk_mul_f32 v[174:175], v[174:175], v[182:183]
	v_pk_mul_f32 v[172:173], v[172:173], v[176:177]
	v_pk_mul_f32 v[174:175], v[174:175], v[178:179]
	v_cvt_pk_bf16_f32 v62, v172, v173
	v_cvt_pk_bf16_f32 v63, v174, v175
	v_add_u32_e32 v241, 0xb0000, v235
	global_store_dwordx4 v241, v[60:63], s[56:57]
	s_branch .LBB0_1200
